# branch tile order made XCD-aware (each XCD owns 8 row blocks x all 8 column tiles)
# speedup vs baseline: 1.0168x; 1.0069x over previous
.LBB0_212:
	v_mov_b32_e32 v0, v1
	v_mbcnt_lo_u32_b32 v0, -1, v0
	v_mbcnt_hi_u32_b32 v0, -1, v0
	v_add_u32_e32 v132, s80, v0
	s_waitcnt vmcnt(0) lgkmcnt(0)
	s_barrier
	v_readlane_b32 s50, v252, 18
	v_readlane_b32 s51, v252, 19
	s_mov_b32 s99, s22
	s_cmpk_eq_u32 s81, 0x200
	s_cbranch_scc0 .Lbr_noremap
	s_and_b32 s98, s22, 7
	s_lshl_b32 s98, s98, 6
	s_lshr_b32 s99, s22, 3
	s_or_b32 s99, s99, s98
.Lbr_noremap:
	s_lshl_b32 s23, s99, 4
	s_and_b32 s23, s23, 0xffffff80
	s_and_b32 s24, s99, 7
	s_lshl_b32 s24, s24, 7
	s_lshl_b32 s25, s24, 1
	s_add_u32 s36, s50, 0xf525000
	s_addc_u32 s37, s51, 0
	s_mov_b64 s[38:39], s[4:5]
	s_mov_b64 s[40:41], s[90:91]
	s_add_u32 s42, s90, 0x80
	s_addc_u32 s43, s91, 0
	s_lshl_b32 vcc_lo, s80, 4
	v_lshrrev_b32_e32 v246, 3, v132
	v_and_b32_e32 v247, 7, v132
	v_bfe_u32 v248, v132, 4, 3
	v_xor_b32_e32 v247, v247, v248
	v_lshlrev_b32_e32 v247, 4, v247
	v_add_u32_e32 v0, s23, v246
	v_lshl_or_b32 v206, v0, 10, v247
	v_add_u32_e32 v207, 0x8000, v206
	v_add_u32_e32 v208, 0x10000, v206
	v_add_u32_e32 v209, 0x18000, v206
	v_mul_u32_u24_e32 v0, 0x1800, v0
	v_add3_u32 v222, v0, s25, v247
	v_add_u32_e32 v223, 0x30000, v222
	v_add_u32_e32 v224, 0x60000, v222
	v_add_u32_e32 v225, 0x90000, v222
	v_add_u32_e32 v0, s24, v246
	v_mul_u32_u24_e32 v0, 0xc00, v0
	v_add_u32_e32 v210, v0, v247
	v_add_u32_e32 v211, 0x18000, v210
	v_add_u32_e32 v212, 0x30000, v210
	v_add_u32_e32 v213, 0x48000, v210
	s_mov_b32 m0, vcc_lo
	s_nop 0
	global_load_lds_dwordx4 v206, s[36:37]
	s_add_u32 m0, vcc_lo, 0x1000
	s_nop 0
	global_load_lds_dwordx4 v207, s[36:37]
	s_add_u32 m0, vcc_lo, 0x2000
	s_nop 0
	global_load_lds_dwordx4 v208, s[36:37]
	s_add_u32 m0, vcc_lo, 0x3000
	s_nop 0
	global_load_lds_dwordx4 v209, s[36:37]
	s_add_u32 m0, vcc_lo, 0x4000
	s_nop 0
	global_load_lds_dwordx4 v210, s[38:39]
	s_add_u32 m0, vcc_lo, 0x5000
	s_nop 0
	global_load_lds_dwordx4 v211, s[38:39]
	s_add_u32 m0, vcc_lo, 0x6000
	s_nop 0
	global_load_lds_dwordx4 v212, s[38:39]
	s_add_u32 m0, vcc_lo, 0x7000
	s_nop 0
	global_load_lds_dwordx4 v213, s[38:39]
	s_add_u32 s36, s36, 0x80
	s_addc_u32 s37, s37, 0
	s_add_u32 s38, s38, 0x80
	s_addc_u32 s39, s39, 0
	v_bfe_u32 v246, v132, 5, 1
	v_bfe_u32 v247, v132, 1, 3
	v_xor_b32_e32 v246, v246, v247
	v_lshlrev_b32_e32 v246, 4, v246
	v_lshrrev_b32_e32 v247, 1, v132
	v_and_b32_e32 v247, 64, v247
	v_and_b32_e32 v248, 31, v132
	v_or_b32_e32 v247, v247, v248
	v_lshl_or_b32 v236, v247, 7, v246
	v_and_b32_e32 v247, 0x5f, v132
	v_lshl_or_b32 v240, v247, 7, v246
	v_add_u32_e32 v240, 0x4000, v240
	v_xor_b32_e32 v237, 0x20, v236
	v_xor_b32_e32 v241, 0x20, v240
	v_xor_b32_e32 v238, 0x40, v236
	v_xor_b32_e32 v242, 0x40, v240
	v_xor_b32_e32 v239, 0x60, v236
	v_xor_b32_e32 v243, 0x60, v240
	v_lshrrev_b32_e32 v246, 1, v132
	v_and_b32_e32 v246, 64, v246
	v_lshrrev_b32_e32 v247, 3, v132
	v_and_or_b32 v246, v247, 4, v246
	v_bfe_u32 v247, v132, 3, 2
	v_lshrrev_b32_e32 v248, 4, v132
	v_and_b32_e32 v248, 2, v248
	v_xor_b32_e32 v247, v247, v248
	v_and_b32_e32 v248, 7, v132
	v_lshlrev_b32_e32 v248, 1, v248
	v_lshl_or_b32 v247, v247, 4, v248
	v_lshl_or_b32 v244, v246, 7, v247
	v_bfe_u32 v247, v132, 6, 1
	v_lshl_or_b32 v244, v247, 14, v244
	v_xor_b32_e32 v245, 16, v244
	v_ashrrev_i32_e32 v184, 4, v132
	v_lshlrev_b32_e32 v185, 3, v132
	v_and_b32_e32 v185, 0x78, v185
	v_mul_u32_u24_e32 v98, 0x110, v246
	v_lshlrev_b32_e32 v247, 1, v132
	v_and_b32_e32 v247, 0x80, v247
	v_and_b32_e32 v248, 31, v132
	v_lshl_or_b32 v247, v248, 1, v247
	v_add_u32_e32 v98, v98, v247
	v_mul_u32_u24_e32 v133, 0x110, v184
	v_lshl_add_u32 v133, v185, 1, v133
	v_mov_b32_e32 v166, 0
	v_mov_b32_e32 v167, 0
	v_mov_b32_e32 v164, 0
	v_mov_b32_e32 v165, 0
	v_mov_b32_e32 v162, 0
	v_mov_b32_e32 v163, 0
	v_mov_b32_e32 v160, 0
	v_mov_b32_e32 v161, 0
	v_mov_b32_e32 v158, 0
	v_mov_b32_e32 v159, 0
	v_mov_b32_e32 v156, 0
	v_mov_b32_e32 v157, 0
	v_mov_b32_e32 v154, 0
	v_mov_b32_e32 v155, 0
	v_mov_b32_e32 v152, 0
	v_mov_b32_e32 v153, 0
	v_mov_b32_e32 v150, 0
	v_mov_b32_e32 v151, 0
	v_mov_b32_e32 v148, 0
	v_mov_b32_e32 v149, 0
	v_mov_b32_e32 v146, 0
	v_mov_b32_e32 v147, 0
	v_mov_b32_e32 v142, 0
	v_mov_b32_e32 v143, 0
	v_mov_b32_e32 v140, 0
	v_mov_b32_e32 v141, 0
	v_mov_b32_e32 v138, 0
	v_mov_b32_e32 v139, 0
	v_mov_b32_e32 v136, 0
	v_mov_b32_e32 v137, 0
	v_mov_b32_e32 v134, 0
	v_mov_b32_e32 v135, 0
	v_mov_b32_e32 v130, 0
	v_mov_b32_e32 v131, 0
	v_mov_b32_e32 v128, 0
	v_mov_b32_e32 v129, 0
	v_mov_b32_e32 v126, 0
	v_mov_b32_e32 v127, 0
	v_mov_b32_e32 v124, 0
	v_mov_b32_e32 v125, 0
	v_mov_b32_e32 v122, 0
	v_mov_b32_e32 v123, 0
	v_mov_b32_e32 v120, 0
	v_mov_b32_e32 v121, 0
	v_mov_b32_e32 v118, 0
	v_mov_b32_e32 v119, 0
	v_mov_b32_e32 v116, 0
	v_mov_b32_e32 v117, 0
	v_mov_b32_e32 v114, 0
	v_mov_b32_e32 v115, 0
	v_mov_b32_e32 v112, 0
	v_mov_b32_e32 v113, 0
	v_mov_b32_e32 v110, 0
	v_mov_b32_e32 v111, 0
	v_mov_b32_e32 v108, 0
	v_mov_b32_e32 v109, 0
	v_mov_b32_e32 v106, 0
	v_mov_b32_e32 v107, 0
	v_mov_b32_e32 v104, 0
	v_mov_b32_e32 v105, 0
	v_mov_b32_e32 v102, 0
	v_mov_b32_e32 v103, 0
	v_mov_b32_e32 v100, 0
	v_mov_b32_e32 v101, 0
	s_waitcnt vmcnt(0)
	s_barrier
	s_add_u32 m0, vcc_lo, 0x8000
	ds_read_b128 v[66:69], v236
	global_load_lds_dwordx4 v206, s[36:37]
	s_setprio 3
	ds_read_b128 v[70:73], v240
	s_add_u32 m0, vcc_lo, 0x9000
	ds_read_b128 v[74:77], v240 offset:4096
	global_load_lds_dwordx4 v207, s[36:37]
	ds_read_b128 v[78:81], v236 offset:4096
	s_add_u32 m0, vcc_lo, 0xa000
	ds_read_b128 v[82:85], v237
	global_load_lds_dwordx4 v208, s[36:37]
	ds_read_b128 v[86:89], v241
	s_add_u32 m0, vcc_lo, 0xb000
	ds_read_b128 v[90:93], v241 offset:4096
	global_load_lds_dwordx4 v209, s[36:37]
	ds_read_b128 v[94:97], v237 offset:4096
	s_waitcnt lgkmcnt(6)
	v_mfma_f32_32x32x16_bf16 v[50:65], v[66:69], v[70:73], 0
	s_add_u32 m0, vcc_lo, 0xc000
	ds_read_b128 v[168:171], v238
	global_load_lds_dwordx4 v210, s[38:39]
	s_waitcnt lgkmcnt(5)
	v_mfma_f32_32x32x16_bf16 v[18:33], v[78:81], v[70:73], 0
	ds_read_b128 v[172:175], v242
	v_mfma_f32_32x32x16_bf16 v[2:17], v[78:81], v[74:77], 0
	s_add_u32 m0, vcc_lo, 0xd000
	ds_read_b128 v[176:179], v242 offset:4096
	global_load_lds_dwordx4 v211, s[38:39]
	v_mfma_f32_32x32x16_bf16 v[34:49], v[66:69], v[74:77], 0
	ds_read_b128 v[180:183], v238 offset:4096
	s_waitcnt lgkmcnt(6)
	v_mfma_f32_32x32x16_bf16 v[50:65], v[82:85], v[86:89], v[50:65]
	s_add_u32 m0, vcc_lo, 0xe000
	ds_read_b128 v[190:193], v239
	global_load_lds_dwordx4 v212, s[38:39]
	s_waitcnt lgkmcnt(5)
	v_mfma_f32_32x32x16_bf16 v[18:33], v[94:97], v[86:89], v[18:33]
	ds_read_b128 v[194:197], v243
	v_mfma_f32_32x32x16_bf16 v[2:17], v[94:97], v[90:93], v[2:17]
	s_add_u32 m0, vcc_lo, 0xf000
	ds_read_b128 v[198:201], v243 offset:4096
	global_load_lds_dwordx4 v213, s[38:39]
	v_mfma_f32_32x32x16_bf16 v[34:49], v[82:85], v[90:93], v[34:49]
	ds_read_b128 v[202:205], v239 offset:4096
	s_add_u32 s36, s36, 0x80
	s_addc_u32 s37, s37, 0
	s_add_u32 s38, s38, 0x80
	s_addc_u32 s39, s39, 0
	s_waitcnt vmcnt(0) lgkmcnt(0)
	s_barrier
	v_mfma_f32_32x32x16_bf16 v[50:65], v[168:171], v[172:175], v[50:65]
	s_mov_b32 m0, vcc_lo
	ds_read_b128 v[66:69], v236 offset:32768
	global_load_lds_dwordx4 v206, s[36:37]
	s_setprio 3
	v_mfma_f32_32x32x16_bf16 v[18:33], v[180:183], v[172:175], v[18:33]
	ds_read_b128 v[70:73], v240 offset:32768
	v_mfma_f32_32x32x16_bf16 v[2:17], v[180:183], v[176:179], v[2:17]
	s_add_u32 m0, vcc_lo, 0x1000
	ds_read_b128 v[74:77], v240 offset:36864
	global_load_lds_dwordx4 v207, s[36:37]
	v_mfma_f32_32x32x16_bf16 v[34:49], v[168:171], v[176:179], v[34:49]
	ds_read_b128 v[78:81], v236 offset:36864
	v_mfma_f32_32x32x16_bf16 v[50:65], v[190:193], v[194:197], v[50:65]
	s_add_u32 m0, vcc_lo, 0x2000
	ds_read_b128 v[82:85], v237 offset:32768
	global_load_lds_dwordx4 v208, s[36:37]
	v_mfma_f32_32x32x16_bf16 v[18:33], v[202:205], v[194:197], v[18:33]
	ds_read_b128 v[86:89], v241 offset:32768
	v_mfma_f32_32x32x16_bf16 v[2:17], v[202:205], v[198:201], v[2:17]
	s_add_u32 m0, vcc_lo, 0x3000
	ds_read_b128 v[90:93], v241 offset:36864
	global_load_lds_dwordx4 v209, s[36:37]
	v_mfma_f32_32x32x16_bf16 v[34:49], v[190:193], v[198:201], v[34:49]
	ds_read_b128 v[94:97], v237 offset:36864
	s_waitcnt lgkmcnt(6)
	v_mfma_f32_32x32x16_bf16 v[50:65], v[66:69], v[70:73], v[50:65]
	s_add_u32 m0, vcc_lo, 0x4000
	ds_read_b128 v[168:171], v238 offset:32768
	global_load_lds_dwordx4 v210, s[38:39]
	s_waitcnt lgkmcnt(5)
	v_mfma_f32_32x32x16_bf16 v[18:33], v[78:81], v[70:73], v[18:33]
	ds_read_b128 v[172:175], v242 offset:32768
	v_mfma_f32_32x32x16_bf16 v[2:17], v[78:81], v[74:77], v[2:17]
	s_add_u32 m0, vcc_lo, 0x5000
	ds_read_b128 v[176:179], v242 offset:36864
	global_load_lds_dwordx4 v211, s[38:39]
	v_mfma_f32_32x32x16_bf16 v[34:49], v[66:69], v[74:77], v[34:49]
	ds_read_b128 v[180:183], v238 offset:36864
	s_waitcnt lgkmcnt(6)
	v_mfma_f32_32x32x16_bf16 v[50:65], v[82:85], v[86:89], v[50:65]
	s_add_u32 m0, vcc_lo, 0x6000
	ds_read_b128 v[190:193], v239 offset:32768
	global_load_lds_dwordx4 v212, s[38:39]
	s_waitcnt lgkmcnt(5)
	v_mfma_f32_32x32x16_bf16 v[18:33], v[94:97], v[86:89], v[18:33]
	ds_read_b128 v[194:197], v243 offset:32768
	v_mfma_f32_32x32x16_bf16 v[2:17], v[94:97], v[90:93], v[2:17]
	s_add_u32 m0, vcc_lo, 0x7000
	ds_read_b128 v[198:201], v243 offset:36864
	global_load_lds_dwordx4 v213, s[38:39]
	v_mfma_f32_32x32x16_bf16 v[34:49], v[82:85], v[90:93], v[34:49]
	ds_read_b128 v[202:205], v239 offset:36864
	s_add_u32 s36, s36, 0x80
	s_addc_u32 s37, s37, 0
	s_add_u32 s38, s38, 0x80
	s_addc_u32 s39, s39, 0
	s_waitcnt vmcnt(0) lgkmcnt(0)
	s_barrier
	v_mfma_f32_32x32x16_bf16 v[50:65], v[168:171], v[172:175], v[50:65]
	s_add_u32 m0, vcc_lo, 0x8000
	ds_read_b128 v[66:69], v236
	global_load_lds_dwordx4 v206, s[36:37]
	s_setprio 3
	v_mfma_f32_32x32x16_bf16 v[18:33], v[180:183], v[172:175], v[18:33]
	ds_read_b128 v[70:73], v240
	v_mfma_f32_32x32x16_bf16 v[2:17], v[180:183], v[176:179], v[2:17]
	s_add_u32 m0, vcc_lo, 0x9000
	ds_read_b128 v[74:77], v240 offset:4096
	global_load_lds_dwordx4 v207, s[36:37]
	v_mfma_f32_32x32x16_bf16 v[34:49], v[168:171], v[176:179], v[34:49]
	ds_read_b128 v[78:81], v236 offset:4096
	v_mfma_f32_32x32x16_bf16 v[50:65], v[190:193], v[194:197], v[50:65]
	s_add_u32 m0, vcc_lo, 0xa000
	ds_read_b128 v[82:85], v237
	global_load_lds_dwordx4 v208, s[36:37]
	v_mfma_f32_32x32x16_bf16 v[18:33], v[202:205], v[194:197], v[18:33]
	ds_read_b128 v[86:89], v241
	v_mfma_f32_32x32x16_bf16 v[2:17], v[202:205], v[198:201], v[2:17]
	s_add_u32 m0, vcc_lo, 0xb000
	ds_read_b128 v[90:93], v241 offset:4096
	global_load_lds_dwordx4 v209, s[36:37]
	v_mfma_f32_32x32x16_bf16 v[34:49], v[190:193], v[198:201], v[34:49]
	ds_read_b128 v[94:97], v237 offset:4096
	s_waitcnt lgkmcnt(6)
	v_mfma_f32_32x32x16_bf16 v[50:65], v[66:69], v[70:73], v[50:65]
	s_add_u32 m0, vcc_lo, 0xc000
	ds_read_b128 v[168:171], v238
	global_load_lds_dwordx4 v210, s[38:39]
	s_waitcnt lgkmcnt(5)
	v_mfma_f32_32x32x16_bf16 v[18:33], v[78:81], v[70:73], v[18:33]
	ds_read_b128 v[172:175], v242
	v_mfma_f32_32x32x16_bf16 v[2:17], v[78:81], v[74:77], v[2:17]
	s_add_u32 m0, vcc_lo, 0xd000
	ds_read_b128 v[176:179], v242 offset:4096
	global_load_lds_dwordx4 v211, s[38:39]
	v_mfma_f32_32x32x16_bf16 v[34:49], v[66:69], v[74:77], v[34:49]
	ds_read_b128 v[180:183], v238 offset:4096
	s_waitcnt lgkmcnt(6)
	v_mfma_f32_32x32x16_bf16 v[50:65], v[82:85], v[86:89], v[50:65]
	s_add_u32 m0, vcc_lo, 0xe000
	ds_read_b128 v[190:193], v239
	global_load_lds_dwordx4 v212, s[38:39]
	s_waitcnt lgkmcnt(5)
	v_mfma_f32_32x32x16_bf16 v[18:33], v[94:97], v[86:89], v[18:33]
	ds_read_b128 v[194:197], v243
	v_mfma_f32_32x32x16_bf16 v[2:17], v[94:97], v[90:93], v[2:17]
	s_add_u32 m0, vcc_lo, 0xf000
	ds_read_b128 v[198:201], v243 offset:4096
	global_load_lds_dwordx4 v213, s[38:39]
	v_mfma_f32_32x32x16_bf16 v[34:49], v[82:85], v[90:93], v[34:49]
	ds_read_b128 v[202:205], v239 offset:4096
	s_add_u32 s36, s36, 0x80
	s_addc_u32 s37, s37, 0
	s_add_u32 s38, s38, 0x80
	s_addc_u32 s39, s39, 0
	s_waitcnt vmcnt(0) lgkmcnt(0)
	s_barrier
	v_mfma_f32_32x32x16_bf16 v[50:65], v[168:171], v[172:175], v[50:65]
	s_mov_b32 m0, vcc_lo
	ds_read_b128 v[66:69], v236 offset:32768
	global_load_lds_dwordx4 v206, s[36:37]
	s_setprio 3
	v_mfma_f32_32x32x16_bf16 v[18:33], v[180:183], v[172:175], v[18:33]
	ds_read_b128 v[70:73], v240 offset:32768
	v_mfma_f32_32x32x16_bf16 v[2:17], v[180:183], v[176:179], v[2:17]
	s_add_u32 m0, vcc_lo, 0x1000
	ds_read_b128 v[74:77], v240 offset:36864
	global_load_lds_dwordx4 v207, s[36:37]
	v_mfma_f32_32x32x16_bf16 v[34:49], v[168:171], v[176:179], v[34:49]
	ds_read_b128 v[78:81], v236 offset:36864
	v_mfma_f32_32x32x16_bf16 v[50:65], v[190:193], v[194:197], v[50:65]
	s_add_u32 m0, vcc_lo, 0x2000
	ds_read_b128 v[82:85], v237 offset:32768
	global_load_lds_dwordx4 v208, s[36:37]
	v_mfma_f32_32x32x16_bf16 v[18:33], v[202:205], v[194:197], v[18:33]
	ds_read_b128 v[86:89], v241 offset:32768
	v_mfma_f32_32x32x16_bf16 v[2:17], v[202:205], v[198:201], v[2:17]
	s_add_u32 m0, vcc_lo, 0x3000
	ds_read_b128 v[90:93], v241 offset:36864
	global_load_lds_dwordx4 v209, s[36:37]
	v_mfma_f32_32x32x16_bf16 v[34:49], v[190:193], v[198:201], v[34:49]
	ds_read_b128 v[94:97], v237 offset:36864
	s_waitcnt lgkmcnt(6)
	v_mfma_f32_32x32x16_bf16 v[50:65], v[66:69], v[70:73], v[50:65]
	s_add_u32 m0, vcc_lo, 0x4000
	ds_read_b128 v[168:171], v238 offset:32768
	global_load_lds_dwordx4 v210, s[38:39]
	s_waitcnt lgkmcnt(5)
	v_mfma_f32_32x32x16_bf16 v[18:33], v[78:81], v[70:73], v[18:33]
	ds_read_b128 v[172:175], v242 offset:32768
	v_mfma_f32_32x32x16_bf16 v[2:17], v[78:81], v[74:77], v[2:17]
	s_add_u32 m0, vcc_lo, 0x5000
	ds_read_b128 v[176:179], v242 offset:36864
	global_load_lds_dwordx4 v211, s[38:39]
	v_mfma_f32_32x32x16_bf16 v[34:49], v[66:69], v[74:77], v[34:49]
	ds_read_b128 v[180:183], v238 offset:36864
	s_waitcnt lgkmcnt(6)
	v_mfma_f32_32x32x16_bf16 v[50:65], v[82:85], v[86:89], v[50:65]
	s_add_u32 m0, vcc_lo, 0x6000
	ds_read_b128 v[190:193], v239 offset:32768
	global_load_lds_dwordx4 v212, s[38:39]
	s_waitcnt lgkmcnt(5)
	v_mfma_f32_32x32x16_bf16 v[18:33], v[94:97], v[86:89], v[18:33]
	ds_read_b128 v[194:197], v243 offset:32768
	v_mfma_f32_32x32x16_bf16 v[2:17], v[94:97], v[90:93], v[2:17]
	s_add_u32 m0, vcc_lo, 0x7000
	ds_read_b128 v[198:201], v243 offset:36864
	global_load_lds_dwordx4 v213, s[38:39]
	v_mfma_f32_32x32x16_bf16 v[34:49], v[82:85], v[90:93], v[34:49]
	ds_read_b128 v[202:205], v239 offset:36864
	s_add_u32 s36, s36, 0x80
	s_addc_u32 s37, s37, 0
	s_add_u32 s38, s38, 0x80
	s_addc_u32 s39, s39, 0
	s_waitcnt vmcnt(0) lgkmcnt(0)
	s_barrier
	v_mfma_f32_32x32x16_bf16 v[50:65], v[168:171], v[172:175], v[50:65]
	s_add_u32 m0, vcc_lo, 0x8000
	ds_read_b128 v[66:69], v236
	global_load_lds_dwordx4 v206, s[36:37]
	s_setprio 3
	v_mfma_f32_32x32x16_bf16 v[18:33], v[180:183], v[172:175], v[18:33]
	ds_read_b128 v[70:73], v240
	v_mfma_f32_32x32x16_bf16 v[2:17], v[180:183], v[176:179], v[2:17]
	s_add_u32 m0, vcc_lo, 0x9000
	ds_read_b128 v[74:77], v240 offset:4096
	global_load_lds_dwordx4 v207, s[36:37]
	v_mfma_f32_32x32x16_bf16 v[34:49], v[168:171], v[176:179], v[34:49]
	ds_read_b128 v[78:81], v236 offset:4096
	v_mfma_f32_32x32x16_bf16 v[50:65], v[190:193], v[194:197], v[50:65]
	s_add_u32 m0, vcc_lo, 0xa000
	ds_read_b128 v[82:85], v237
	global_load_lds_dwordx4 v208, s[36:37]
	v_mfma_f32_32x32x16_bf16 v[18:33], v[202:205], v[194:197], v[18:33]
	ds_read_b128 v[86:89], v241
	v_mfma_f32_32x32x16_bf16 v[2:17], v[202:205], v[198:201], v[2:17]
	s_add_u32 m0, vcc_lo, 0xb000
	ds_read_b128 v[90:93], v241 offset:4096
	global_load_lds_dwordx4 v209, s[36:37]
	v_mfma_f32_32x32x16_bf16 v[34:49], v[190:193], v[198:201], v[34:49]
	ds_read_b128 v[94:97], v237 offset:4096
	s_waitcnt lgkmcnt(6)
	v_mfma_f32_32x32x16_bf16 v[50:65], v[66:69], v[70:73], v[50:65]
	s_add_u32 m0, vcc_lo, 0xc000
	ds_read_b128 v[168:171], v238
	global_load_lds_dwordx4 v210, s[38:39]
	s_waitcnt lgkmcnt(5)
	v_mfma_f32_32x32x16_bf16 v[18:33], v[78:81], v[70:73], v[18:33]
	ds_read_b128 v[172:175], v242
	v_mfma_f32_32x32x16_bf16 v[2:17], v[78:81], v[74:77], v[2:17]
	s_add_u32 m0, vcc_lo, 0xd000
	ds_read_b128 v[176:179], v242 offset:4096
	global_load_lds_dwordx4 v211, s[38:39]
	v_mfma_f32_32x32x16_bf16 v[34:49], v[66:69], v[74:77], v[34:49]
	ds_read_b128 v[180:183], v238 offset:4096
	s_waitcnt lgkmcnt(6)
	v_mfma_f32_32x32x16_bf16 v[50:65], v[82:85], v[86:89], v[50:65]
	s_add_u32 m0, vcc_lo, 0xe000
	ds_read_b128 v[190:193], v239
	global_load_lds_dwordx4 v212, s[38:39]
	s_waitcnt lgkmcnt(5)
	v_mfma_f32_32x32x16_bf16 v[18:33], v[94:97], v[86:89], v[18:33]
	ds_read_b128 v[194:197], v243
	v_mfma_f32_32x32x16_bf16 v[2:17], v[94:97], v[90:93], v[2:17]
	s_add_u32 m0, vcc_lo, 0xf000
	ds_read_b128 v[198:201], v243 offset:4096
	global_load_lds_dwordx4 v213, s[38:39]
	v_mfma_f32_32x32x16_bf16 v[34:49], v[82:85], v[90:93], v[34:49]
	ds_read_b128 v[202:205], v239 offset:4096
	s_add_u32 s36, s36, 0x80
	s_addc_u32 s37, s37, 0
	s_add_u32 s38, s38, 0x80
	s_addc_u32 s39, s39, 0
	s_waitcnt vmcnt(0) lgkmcnt(0)
	s_barrier
	v_mfma_f32_32x32x16_bf16 v[50:65], v[168:171], v[172:175], v[50:65]
	s_mov_b32 m0, vcc_lo
	ds_read_b128 v[66:69], v236 offset:32768
	global_load_lds_dwordx4 v206, s[36:37]
	s_setprio 3
	v_mfma_f32_32x32x16_bf16 v[18:33], v[180:183], v[172:175], v[18:33]
	ds_read_b128 v[70:73], v240 offset:32768
	v_mfma_f32_32x32x16_bf16 v[2:17], v[180:183], v[176:179], v[2:17]
	s_add_u32 m0, vcc_lo, 0x1000
	ds_read_b128 v[74:77], v240 offset:36864
	global_load_lds_dwordx4 v207, s[36:37]
	v_mfma_f32_32x32x16_bf16 v[34:49], v[168:171], v[176:179], v[34:49]
	ds_read_b128 v[78:81], v236 offset:36864
	v_mfma_f32_32x32x16_bf16 v[50:65], v[190:193], v[194:197], v[50:65]
	s_add_u32 m0, vcc_lo, 0x2000
	ds_read_b128 v[82:85], v237 offset:32768
	global_load_lds_dwordx4 v208, s[36:37]
	v_mfma_f32_32x32x16_bf16 v[18:33], v[202:205], v[194:197], v[18:33]
	ds_read_b128 v[86:89], v241 offset:32768
	v_mfma_f32_32x32x16_bf16 v[2:17], v[202:205], v[198:201], v[2:17]
	s_add_u32 m0, vcc_lo, 0x3000
	ds_read_b128 v[90:93], v241 offset:36864
	global_load_lds_dwordx4 v209, s[36:37]
	v_mfma_f32_32x32x16_bf16 v[34:49], v[190:193], v[198:201], v[34:49]
	ds_read_b128 v[94:97], v237 offset:36864
	s_waitcnt lgkmcnt(6)
	v_mfma_f32_32x32x16_bf16 v[50:65], v[66:69], v[70:73], v[50:65]
	s_add_u32 m0, vcc_lo, 0x4000
	ds_read_b128 v[168:171], v238 offset:32768
	global_load_lds_dwordx4 v210, s[38:39]
	s_waitcnt lgkmcnt(5)
	v_mfma_f32_32x32x16_bf16 v[18:33], v[78:81], v[70:73], v[18:33]
	ds_read_b128 v[172:175], v242 offset:32768
	v_mfma_f32_32x32x16_bf16 v[2:17], v[78:81], v[74:77], v[2:17]
	s_add_u32 m0, vcc_lo, 0x5000
	ds_read_b128 v[176:179], v242 offset:36864
	global_load_lds_dwordx4 v211, s[38:39]
	v_mfma_f32_32x32x16_bf16 v[34:49], v[66:69], v[74:77], v[34:49]
	ds_read_b128 v[180:183], v238 offset:36864
	s_waitcnt lgkmcnt(6)
	v_mfma_f32_32x32x16_bf16 v[50:65], v[82:85], v[86:89], v[50:65]
	s_add_u32 m0, vcc_lo, 0x6000
	ds_read_b128 v[190:193], v239 offset:32768
	global_load_lds_dwordx4 v212, s[38:39]
	s_waitcnt lgkmcnt(5)
	v_mfma_f32_32x32x16_bf16 v[18:33], v[94:97], v[86:89], v[18:33]
	ds_read_b128 v[194:197], v243 offset:32768
	v_mfma_f32_32x32x16_bf16 v[2:17], v[94:97], v[90:93], v[2:17]
	s_add_u32 m0, vcc_lo, 0x7000
	ds_read_b128 v[198:201], v243 offset:36864
	global_load_lds_dwordx4 v213, s[38:39]
	v_mfma_f32_32x32x16_bf16 v[34:49], v[82:85], v[90:93], v[34:49]
	ds_read_b128 v[202:205], v239 offset:36864
	s_add_u32 s36, s36, 0x80
	s_addc_u32 s37, s37, 0
	s_add_u32 s38, s38, 0x80
	s_addc_u32 s39, s39, 0
	s_waitcnt vmcnt(0) lgkmcnt(0)
	s_barrier
	v_mfma_f32_32x32x16_bf16 v[50:65], v[168:171], v[172:175], v[50:65]
	s_add_u32 m0, vcc_lo, 0x8000
	ds_read_b128 v[66:69], v236
	global_load_lds_dwordx4 v206, s[36:37]
	s_setprio 3
	v_mfma_f32_32x32x16_bf16 v[18:33], v[180:183], v[172:175], v[18:33]
	ds_read_b128 v[70:73], v240
	v_mfma_f32_32x32x16_bf16 v[2:17], v[180:183], v[176:179], v[2:17]
	s_add_u32 m0, vcc_lo, 0x9000
	ds_read_b128 v[74:77], v240 offset:4096
	global_load_lds_dwordx4 v207, s[36:37]
	v_mfma_f32_32x32x16_bf16 v[34:49], v[168:171], v[176:179], v[34:49]
	ds_read_b128 v[78:81], v236 offset:4096
	v_mfma_f32_32x32x16_bf16 v[50:65], v[190:193], v[194:197], v[50:65]
	s_add_u32 m0, vcc_lo, 0xa000
	ds_read_b128 v[82:85], v237
	global_load_lds_dwordx4 v208, s[36:37]
	v_mfma_f32_32x32x16_bf16 v[18:33], v[202:205], v[194:197], v[18:33]
	ds_read_b128 v[86:89], v241
	v_mfma_f32_32x32x16_bf16 v[2:17], v[202:205], v[198:201], v[2:17]
	s_add_u32 m0, vcc_lo, 0xb000
	ds_read_b128 v[90:93], v241 offset:4096
	global_load_lds_dwordx4 v209, s[36:37]
	v_mfma_f32_32x32x16_bf16 v[34:49], v[190:193], v[198:201], v[34:49]
	ds_read_b128 v[94:97], v237 offset:4096
	s_waitcnt lgkmcnt(6)
	v_mfma_f32_32x32x16_bf16 v[50:65], v[66:69], v[70:73], v[50:65]
	s_add_u32 m0, vcc_lo, 0xc000
	ds_read_b128 v[168:171], v238
	global_load_lds_dwordx4 v210, s[38:39]
	s_waitcnt lgkmcnt(5)
	v_mfma_f32_32x32x16_bf16 v[18:33], v[78:81], v[70:73], v[18:33]
	ds_read_b128 v[172:175], v242
	v_mfma_f32_32x32x16_bf16 v[2:17], v[78:81], v[74:77], v[2:17]
	s_add_u32 m0, vcc_lo, 0xd000
	ds_read_b128 v[176:179], v242 offset:4096
	global_load_lds_dwordx4 v211, s[38:39]
	v_mfma_f32_32x32x16_bf16 v[34:49], v[66:69], v[74:77], v[34:49]
	ds_read_b128 v[180:183], v238 offset:4096
	s_waitcnt lgkmcnt(6)
	v_mfma_f32_32x32x16_bf16 v[50:65], v[82:85], v[86:89], v[50:65]
	s_add_u32 m0, vcc_lo, 0xe000
	ds_read_b128 v[190:193], v239
	global_load_lds_dwordx4 v212, s[38:39]
	s_waitcnt lgkmcnt(5)
	v_mfma_f32_32x32x16_bf16 v[18:33], v[94:97], v[86:89], v[18:33]
	ds_read_b128 v[194:197], v243
	v_mfma_f32_32x32x16_bf16 v[2:17], v[94:97], v[90:93], v[2:17]
	s_add_u32 m0, vcc_lo, 0xf000
	ds_read_b128 v[198:201], v243 offset:4096
	global_load_lds_dwordx4 v213, s[38:39]
	v_mfma_f32_32x32x16_bf16 v[34:49], v[82:85], v[90:93], v[34:49]
	ds_read_b128 v[202:205], v239 offset:4096
	s_add_u32 s38, s38, 0x80
	s_addc_u32 s39, s39, 0
	s_add_u32 s36, s50, 0x5c25000
	s_addc_u32 s37, s51, 0
	s_waitcnt vmcnt(0) lgkmcnt(0)
	s_barrier
	v_mfma_f32_32x32x16_bf16 v[50:65], v[168:171], v[172:175], v[50:65]
	s_mov_b32 m0, vcc_lo
	ds_read_b128 v[66:69], v236 offset:32768
	global_load_lds_dwordx4 v222, s[40:41]
	s_setprio 3
	v_mfma_f32_32x32x16_bf16 v[18:33], v[180:183], v[172:175], v[18:33]
	ds_read_b128 v[70:73], v240 offset:32768
	v_mfma_f32_32x32x16_bf16 v[2:17], v[180:183], v[176:179], v[2:17]
	s_add_u32 m0, vcc_lo, 0x1000
	ds_read_b128 v[74:77], v240 offset:36864
	global_load_lds_dwordx4 v223, s[40:41]
	v_mfma_f32_32x32x16_bf16 v[34:49], v[168:171], v[176:179], v[34:49]
	ds_read_b128 v[78:81], v236 offset:36864
	v_mfma_f32_32x32x16_bf16 v[50:65], v[190:193], v[194:197], v[50:65]
	s_add_u32 m0, vcc_lo, 0x2000
	ds_read_b128 v[82:85], v237 offset:32768
	global_load_lds_dwordx4 v224, s[40:41]
	v_mfma_f32_32x32x16_bf16 v[18:33], v[202:205], v[194:197], v[18:33]
	ds_read_b128 v[86:89], v241 offset:32768
	v_mfma_f32_32x32x16_bf16 v[2:17], v[202:205], v[198:201], v[2:17]
	s_add_u32 m0, vcc_lo, 0x3000
	ds_read_b128 v[90:93], v241 offset:36864
	global_load_lds_dwordx4 v225, s[40:41]
	v_mfma_f32_32x32x16_bf16 v[34:49], v[190:193], v[198:201], v[34:49]
	ds_read_b128 v[94:97], v237 offset:36864
	s_waitcnt lgkmcnt(6)
	v_mfma_f32_32x32x16_bf16 v[50:65], v[66:69], v[70:73], v[50:65]
	s_add_u32 m0, vcc_lo, 0x4000
	ds_read_b128 v[168:171], v238 offset:32768
	global_load_lds_dwordx4 v222, s[42:43]
	s_waitcnt lgkmcnt(5)
	v_mfma_f32_32x32x16_bf16 v[18:33], v[78:81], v[70:73], v[18:33]
	ds_read_b128 v[172:175], v242 offset:32768
	v_mfma_f32_32x32x16_bf16 v[2:17], v[78:81], v[74:77], v[2:17]
	s_add_u32 m0, vcc_lo, 0x5000
	ds_read_b128 v[176:179], v242 offset:36864
	global_load_lds_dwordx4 v223, s[42:43]
	v_mfma_f32_32x32x16_bf16 v[34:49], v[66:69], v[74:77], v[34:49]
	ds_read_b128 v[180:183], v238 offset:36864
	s_waitcnt lgkmcnt(6)
	v_mfma_f32_32x32x16_bf16 v[50:65], v[82:85], v[86:89], v[50:65]
	s_add_u32 m0, vcc_lo, 0x6000
	ds_read_b128 v[190:193], v239 offset:32768
	global_load_lds_dwordx4 v224, s[42:43]
	s_waitcnt lgkmcnt(5)
	v_mfma_f32_32x32x16_bf16 v[18:33], v[94:97], v[86:89], v[18:33]
	ds_read_b128 v[194:197], v243 offset:32768
	v_mfma_f32_32x32x16_bf16 v[2:17], v[94:97], v[90:93], v[2:17]
	s_add_u32 m0, vcc_lo, 0x7000
	ds_read_b128 v[198:201], v243 offset:36864
	global_load_lds_dwordx4 v225, s[42:43]
	v_mfma_f32_32x32x16_bf16 v[34:49], v[82:85], v[90:93], v[34:49]
	ds_read_b128 v[202:205], v239 offset:36864
	s_add_u32 s40, s40, 0x800
	s_addc_u32 s41, s41, 0
	s_add_u32 s42, s42, 0x800
	s_addc_u32 s43, s43, 0
	s_waitcnt vmcnt(0) lgkmcnt(0)
	s_barrier
	s_add_u32 m0, vcc_lo, 0x8000
	v_mfma_f32_32x32x16_bf16 v[50:65], v[168:171], v[172:175], v[50:65]
	global_load_lds_dwordx4 v206, s[36:37]
	s_add_u32 m0, vcc_lo, 0x9000
	v_mfma_f32_32x32x16_bf16 v[18:33], v[180:183], v[172:175], v[18:33]
	global_load_lds_dwordx4 v207, s[36:37]
	s_add_u32 m0, vcc_lo, 0xa000
	v_mfma_f32_32x32x16_bf16 v[2:17], v[180:183], v[176:179], v[2:17]
	global_load_lds_dwordx4 v208, s[36:37]
	s_add_u32 m0, vcc_lo, 0xb000
	v_mfma_f32_32x32x16_bf16 v[34:49], v[168:171], v[176:179], v[34:49]
	global_load_lds_dwordx4 v209, s[36:37]
	s_add_u32 m0, vcc_lo, 0xc000
	v_mfma_f32_32x32x16_bf16 v[50:65], v[190:193], v[194:197], v[50:65]
	global_load_lds_dwordx4 v210, s[38:39]
	s_add_u32 m0, vcc_lo, 0xd000
	v_mfma_f32_32x32x16_bf16 v[18:33], v[202:205], v[194:197], v[18:33]
	global_load_lds_dwordx4 v211, s[38:39]
	s_add_u32 m0, vcc_lo, 0xe000
	v_mfma_f32_32x32x16_bf16 v[2:17], v[202:205], v[198:201], v[2:17]
	global_load_lds_dwordx4 v212, s[38:39]
	s_add_u32 m0, vcc_lo, 0xf000
	v_mfma_f32_32x32x16_bf16 v[34:49], v[190:193], v[198:201], v[34:49]
	global_load_lds_dwordx4 v213, s[38:39]
	s_add_u32 s36, s36, 0x80
	s_addc_u32 s37, s37, 0
	s_add_u32 s38, s38, 0x80
	s_addc_u32 s39, s39, 0
	s_setprio 0
	ds_read_u16 v66, v244 offset:0
	ds_read_u16 v67, v244 offset:128
	ds_read_u16 v68, v245 offset:256
	ds_read_u16 v69, v245 offset:384
	ds_read_u16 v70, v244 offset:1088
	ds_read_u16 v71, v244 offset:1216
	ds_read_u16 v72, v245 offset:1344
	ds_read_u16 v73, v245 offset:1472
	s_nop 7
	s_nop 7
	ds_read_u16 v74, v244 offset:2048
	ds_read_u16 v75, v244 offset:2176
	ds_read_u16 v76, v245 offset:2304
	ds_read_u16 v77, v245 offset:2432
	ds_read_u16 v78, v244 offset:3136
	ds_read_u16 v79, v244 offset:3264
	ds_read_u16 v80, v245 offset:3392
	ds_read_u16 v81, v245 offset:3520
	s_waitcnt lgkmcnt(8)
	v_lshlrev_b32_e32 v66, 16, v66
	v_lshlrev_b32_e32 v67, 16, v67
	v_lshlrev_b32_e32 v68, 16, v68
	v_lshlrev_b32_e32 v69, 16, v69
	v_mul_f32_e32 v66, 0xbfb8aa3b, v66
	v_mul_f32_e32 v67, 0xbfb8aa3b, v67
	v_mul_f32_e32 v68, 0xbfb8aa3b, v68
	v_mul_f32_e32 v69, 0xbfb8aa3b, v69
	v_exp_f32_e32 v66, v66
	v_exp_f32_e32 v67, v67
	v_exp_f32_e32 v68, v68
	v_exp_f32_e32 v69, v69
	v_add_f32_e32 v66, 1.0, v66
	v_add_f32_e32 v67, 1.0, v67
	v_add_f32_e32 v68, 1.0, v68
	v_add_f32_e32 v69, 1.0, v69
	v_rcp_f32_e32 v66, v66
	v_rcp_f32_e32 v67, v67
	v_rcp_f32_e32 v68, v68
	v_rcp_f32_e32 v69, v69
	s_nop 0
	v_pk_fma_f32 v[166:167], v[50:51], v[66:67], v[166:167]
	v_pk_fma_f32 v[164:165], v[52:53], v[68:69], v[164:165]
	v_lshlrev_b32_e32 v70, 16, v70
	v_lshlrev_b32_e32 v71, 16, v71
	v_lshlrev_b32_e32 v72, 16, v72
	v_lshlrev_b32_e32 v73, 16, v73
	v_mul_f32_e32 v70, 0xbfb8aa3b, v70
	v_mul_f32_e32 v71, 0xbfb8aa3b, v71
	v_mul_f32_e32 v72, 0xbfb8aa3b, v72
	v_mul_f32_e32 v73, 0xbfb8aa3b, v73
	v_exp_f32_e32 v70, v70
	v_exp_f32_e32 v71, v71
	v_exp_f32_e32 v72, v72
	v_exp_f32_e32 v73, v73
	v_add_f32_e32 v70, 1.0, v70
	v_add_f32_e32 v71, 1.0, v71
	v_add_f32_e32 v72, 1.0, v72
	v_add_f32_e32 v73, 1.0, v73
	v_rcp_f32_e32 v70, v70
	v_rcp_f32_e32 v71, v71
	v_rcp_f32_e32 v72, v72
	v_rcp_f32_e32 v73, v73
	s_nop 0
	v_pk_fma_f32 v[162:163], v[54:55], v[70:71], v[162:163]
	v_pk_fma_f32 v[160:161], v[56:57], v[72:73], v[160:161]
	ds_read_u16 v82, v244 offset:4096
	ds_read_u16 v83, v244 offset:4224
	ds_read_u16 v84, v245 offset:4352
	ds_read_u16 v85, v245 offset:4480
	ds_read_u16 v86, v244 offset:5184
	ds_read_u16 v87, v244 offset:5312
	ds_read_u16 v88, v245 offset:5440
	ds_read_u16 v89, v245 offset:5568
	s_waitcnt lgkmcnt(8)
	v_lshlrev_b32_e32 v74, 16, v74
	v_lshlrev_b32_e32 v75, 16, v75
	v_lshlrev_b32_e32 v76, 16, v76
	v_lshlrev_b32_e32 v77, 16, v77
	v_mul_f32_e32 v74, 0xbfb8aa3b, v74
	v_mul_f32_e32 v75, 0xbfb8aa3b, v75
	v_mul_f32_e32 v76, 0xbfb8aa3b, v76
	v_mul_f32_e32 v77, 0xbfb8aa3b, v77
	v_exp_f32_e32 v74, v74
	v_exp_f32_e32 v75, v75
	v_exp_f32_e32 v76, v76
	v_exp_f32_e32 v77, v77
	v_add_f32_e32 v74, 1.0, v74
	v_add_f32_e32 v75, 1.0, v75
	v_add_f32_e32 v76, 1.0, v76
	v_add_f32_e32 v77, 1.0, v77
	v_rcp_f32_e32 v74, v74
	v_rcp_f32_e32 v75, v75
	v_rcp_f32_e32 v76, v76
	v_rcp_f32_e32 v77, v77
	s_nop 0
	v_pk_fma_f32 v[158:159], v[58:59], v[74:75], v[158:159]
	v_pk_fma_f32 v[156:157], v[60:61], v[76:77], v[156:157]
	v_lshlrev_b32_e32 v78, 16, v78
	v_lshlrev_b32_e32 v79, 16, v79
	v_lshlrev_b32_e32 v80, 16, v80
	v_lshlrev_b32_e32 v81, 16, v81
	v_mul_f32_e32 v78, 0xbfb8aa3b, v78
	v_mul_f32_e32 v79, 0xbfb8aa3b, v79
	v_mul_f32_e32 v80, 0xbfb8aa3b, v80
	v_mul_f32_e32 v81, 0xbfb8aa3b, v81
	v_exp_f32_e32 v78, v78
	v_exp_f32_e32 v79, v79
	v_exp_f32_e32 v80, v80
	v_exp_f32_e32 v81, v81
	v_add_f32_e32 v78, 1.0, v78
	v_add_f32_e32 v79, 1.0, v79
	v_add_f32_e32 v80, 1.0, v80
	v_add_f32_e32 v81, 1.0, v81
	v_rcp_f32_e32 v78, v78
	v_rcp_f32_e32 v79, v79
	v_rcp_f32_e32 v80, v80
	v_rcp_f32_e32 v81, v81
	s_nop 0
	v_pk_fma_f32 v[154:155], v[62:63], v[78:79], v[154:155]
	v_pk_fma_f32 v[152:153], v[64:65], v[80:81], v[152:153]
	ds_read_u16 v90, v244 offset:6144
	ds_read_u16 v91, v244 offset:6272
	ds_read_u16 v92, v245 offset:6400
	ds_read_u16 v93, v245 offset:6528
	ds_read_u16 v94, v244 offset:7232
	ds_read_u16 v95, v244 offset:7360
	ds_read_u16 v96, v245 offset:7488
	ds_read_u16 v97, v245 offset:7616
	s_waitcnt lgkmcnt(8)
	v_lshlrev_b32_e32 v82, 16, v82
	v_lshlrev_b32_e32 v83, 16, v83
	v_lshlrev_b32_e32 v84, 16, v84
	v_lshlrev_b32_e32 v85, 16, v85
	v_mul_f32_e32 v82, 0xbfb8aa3b, v82
	v_mul_f32_e32 v83, 0xbfb8aa3b, v83
	v_mul_f32_e32 v84, 0xbfb8aa3b, v84
	v_mul_f32_e32 v85, 0xbfb8aa3b, v85
	v_exp_f32_e32 v82, v82
	v_exp_f32_e32 v83, v83
	v_exp_f32_e32 v84, v84
	v_exp_f32_e32 v85, v85
	v_add_f32_e32 v82, 1.0, v82
	v_add_f32_e32 v83, 1.0, v83
	v_add_f32_e32 v84, 1.0, v84
	v_add_f32_e32 v85, 1.0, v85
	v_rcp_f32_e32 v82, v82
	v_rcp_f32_e32 v83, v83
	v_rcp_f32_e32 v84, v84
	v_rcp_f32_e32 v85, v85
	s_nop 0
	v_pk_fma_f32 v[130:131], v[18:19], v[82:83], v[130:131]
	v_pk_fma_f32 v[128:129], v[20:21], v[84:85], v[128:129]
	v_lshlrev_b32_e32 v86, 16, v86
	v_lshlrev_b32_e32 v87, 16, v87
	v_lshlrev_b32_e32 v88, 16, v88
	v_lshlrev_b32_e32 v89, 16, v89
	v_mul_f32_e32 v86, 0xbfb8aa3b, v86
	v_mul_f32_e32 v87, 0xbfb8aa3b, v87
	v_mul_f32_e32 v88, 0xbfb8aa3b, v88
	v_mul_f32_e32 v89, 0xbfb8aa3b, v89
	v_exp_f32_e32 v86, v86
	v_exp_f32_e32 v87, v87
	v_exp_f32_e32 v88, v88
	v_exp_f32_e32 v89, v89
	v_add_f32_e32 v86, 1.0, v86
	v_add_f32_e32 v87, 1.0, v87
	v_add_f32_e32 v88, 1.0, v88
	v_add_f32_e32 v89, 1.0, v89
	v_rcp_f32_e32 v86, v86
	v_rcp_f32_e32 v87, v87
	v_rcp_f32_e32 v88, v88
	v_rcp_f32_e32 v89, v89
	s_nop 0
	v_pk_fma_f32 v[126:127], v[22:23], v[86:87], v[126:127]
	v_pk_fma_f32 v[124:125], v[24:25], v[88:89], v[124:125]
	ds_read_u16 v168, v244 offset:4160
	ds_read_u16 v169, v244 offset:4288
	ds_read_u16 v170, v245 offset:4416
	ds_read_u16 v171, v245 offset:4544
	ds_read_u16 v172, v244 offset:5120
	ds_read_u16 v173, v244 offset:5248
	ds_read_u16 v174, v245 offset:5376
	ds_read_u16 v175, v245 offset:5504
	s_waitcnt lgkmcnt(8)
	v_lshlrev_b32_e32 v90, 16, v90
	v_lshlrev_b32_e32 v91, 16, v91
	v_lshlrev_b32_e32 v92, 16, v92
	v_lshlrev_b32_e32 v93, 16, v93
	v_mul_f32_e32 v90, 0xbfb8aa3b, v90
	v_mul_f32_e32 v91, 0xbfb8aa3b, v91
	v_mul_f32_e32 v92, 0xbfb8aa3b, v92
	v_mul_f32_e32 v93, 0xbfb8aa3b, v93
	v_exp_f32_e32 v90, v90
	v_exp_f32_e32 v91, v91
	v_exp_f32_e32 v92, v92
	v_exp_f32_e32 v93, v93
	v_add_f32_e32 v90, 1.0, v90
	v_add_f32_e32 v91, 1.0, v91
	v_add_f32_e32 v92, 1.0, v92
	v_add_f32_e32 v93, 1.0, v93
	v_rcp_f32_e32 v90, v90
	v_rcp_f32_e32 v91, v91
	v_rcp_f32_e32 v92, v92
	v_rcp_f32_e32 v93, v93
	s_nop 0
	v_pk_fma_f32 v[122:123], v[26:27], v[90:91], v[122:123]
	v_pk_fma_f32 v[120:121], v[28:29], v[92:93], v[120:121]
	v_lshlrev_b32_e32 v94, 16, v94
	v_lshlrev_b32_e32 v95, 16, v95
	v_lshlrev_b32_e32 v96, 16, v96
	v_lshlrev_b32_e32 v97, 16, v97
	v_mul_f32_e32 v94, 0xbfb8aa3b, v94
	v_mul_f32_e32 v95, 0xbfb8aa3b, v95
	v_mul_f32_e32 v96, 0xbfb8aa3b, v96
	v_mul_f32_e32 v97, 0xbfb8aa3b, v97
	v_exp_f32_e32 v94, v94
	v_exp_f32_e32 v95, v95
	v_exp_f32_e32 v96, v96
	v_exp_f32_e32 v97, v97
	v_add_f32_e32 v94, 1.0, v94
	v_add_f32_e32 v95, 1.0, v95
	v_add_f32_e32 v96, 1.0, v96
	v_add_f32_e32 v97, 1.0, v97
	v_rcp_f32_e32 v94, v94
	v_rcp_f32_e32 v95, v95
	v_rcp_f32_e32 v96, v96
	v_rcp_f32_e32 v97, v97
	s_nop 0
	v_pk_fma_f32 v[118:119], v[30:31], v[94:95], v[118:119]
	v_pk_fma_f32 v[116:117], v[32:33], v[96:97], v[116:117]
	ds_read_u16 v176, v244 offset:6208
	ds_read_u16 v177, v244 offset:6336
	ds_read_u16 v178, v245 offset:6464
	ds_read_u16 v179, v245 offset:6592
	ds_read_u16 v180, v244 offset:7168
	ds_read_u16 v181, v244 offset:7296
	ds_read_u16 v182, v245 offset:7424
	ds_read_u16 v183, v245 offset:7552
	s_waitcnt lgkmcnt(8)
	v_lshlrev_b32_e32 v168, 16, v168
	v_lshlrev_b32_e32 v169, 16, v169
	v_lshlrev_b32_e32 v170, 16, v170
	v_lshlrev_b32_e32 v171, 16, v171
	v_mul_f32_e32 v168, 0xbfb8aa3b, v168
	v_mul_f32_e32 v169, 0xbfb8aa3b, v169
	v_mul_f32_e32 v170, 0xbfb8aa3b, v170
	v_mul_f32_e32 v171, 0xbfb8aa3b, v171
	v_exp_f32_e32 v168, v168
	v_exp_f32_e32 v169, v169
	v_exp_f32_e32 v170, v170
	v_exp_f32_e32 v171, v171
	v_add_f32_e32 v168, 1.0, v168
	v_add_f32_e32 v169, 1.0, v169
	v_add_f32_e32 v170, 1.0, v170
	v_add_f32_e32 v171, 1.0, v171
	v_rcp_f32_e32 v168, v168
	v_rcp_f32_e32 v169, v169
	v_rcp_f32_e32 v170, v170
	v_rcp_f32_e32 v171, v171
	s_nop 0
	v_pk_fma_f32 v[114:115], v[2:3], v[168:169], v[114:115]
	v_pk_fma_f32 v[112:113], v[4:5], v[170:171], v[112:113]
	v_lshlrev_b32_e32 v172, 16, v172
	v_lshlrev_b32_e32 v173, 16, v173
	v_lshlrev_b32_e32 v174, 16, v174
	v_lshlrev_b32_e32 v175, 16, v175
	v_mul_f32_e32 v172, 0xbfb8aa3b, v172
	v_mul_f32_e32 v173, 0xbfb8aa3b, v173
	v_mul_f32_e32 v174, 0xbfb8aa3b, v174
	v_mul_f32_e32 v175, 0xbfb8aa3b, v175
	v_exp_f32_e32 v172, v172
	v_exp_f32_e32 v173, v173
	v_exp_f32_e32 v174, v174
	v_exp_f32_e32 v175, v175
	v_add_f32_e32 v172, 1.0, v172
	v_add_f32_e32 v173, 1.0, v173
	v_add_f32_e32 v174, 1.0, v174
	v_add_f32_e32 v175, 1.0, v175
	v_rcp_f32_e32 v172, v172
	v_rcp_f32_e32 v173, v173
	v_rcp_f32_e32 v174, v174
	v_rcp_f32_e32 v175, v175
	s_nop 0
	v_pk_fma_f32 v[110:111], v[6:7], v[172:173], v[110:111]
	v_pk_fma_f32 v[108:109], v[8:9], v[174:175], v[108:109]
	ds_read_u16 v190, v244 offset:64
	ds_read_u16 v191, v244 offset:192
	ds_read_u16 v192, v245 offset:320
	ds_read_u16 v193, v245 offset:448
	ds_read_u16 v194, v244 offset:1024
	ds_read_u16 v195, v244 offset:1152
	ds_read_u16 v196, v245 offset:1280
	ds_read_u16 v197, v245 offset:1408
	s_waitcnt lgkmcnt(8)
	v_lshlrev_b32_e32 v176, 16, v176
	v_lshlrev_b32_e32 v177, 16, v177
	v_lshlrev_b32_e32 v178, 16, v178
	v_lshlrev_b32_e32 v179, 16, v179
	v_mul_f32_e32 v176, 0xbfb8aa3b, v176
	v_mul_f32_e32 v177, 0xbfb8aa3b, v177
	v_mul_f32_e32 v178, 0xbfb8aa3b, v178
	v_mul_f32_e32 v179, 0xbfb8aa3b, v179
	v_exp_f32_e32 v176, v176
	v_exp_f32_e32 v177, v177
	v_exp_f32_e32 v178, v178
	v_exp_f32_e32 v179, v179
	v_add_f32_e32 v176, 1.0, v176
	v_add_f32_e32 v177, 1.0, v177
	v_add_f32_e32 v178, 1.0, v178
	v_add_f32_e32 v179, 1.0, v179
	v_rcp_f32_e32 v176, v176
	v_rcp_f32_e32 v177, v177
	v_rcp_f32_e32 v178, v178
	v_rcp_f32_e32 v179, v179
	s_nop 0
	v_pk_fma_f32 v[106:107], v[10:11], v[176:177], v[106:107]
	v_pk_fma_f32 v[104:105], v[12:13], v[178:179], v[104:105]
	v_lshlrev_b32_e32 v180, 16, v180
	v_lshlrev_b32_e32 v181, 16, v181
	v_lshlrev_b32_e32 v182, 16, v182
	v_lshlrev_b32_e32 v183, 16, v183
	v_mul_f32_e32 v180, 0xbfb8aa3b, v180
	v_mul_f32_e32 v181, 0xbfb8aa3b, v181
	v_mul_f32_e32 v182, 0xbfb8aa3b, v182
	v_mul_f32_e32 v183, 0xbfb8aa3b, v183
	v_exp_f32_e32 v180, v180
	v_exp_f32_e32 v181, v181
	v_exp_f32_e32 v182, v182
	v_exp_f32_e32 v183, v183
	v_add_f32_e32 v180, 1.0, v180
	v_add_f32_e32 v181, 1.0, v181
	v_add_f32_e32 v182, 1.0, v182
	v_add_f32_e32 v183, 1.0, v183
	v_rcp_f32_e32 v180, v180
	v_rcp_f32_e32 v181, v181
	v_rcp_f32_e32 v182, v182
	v_rcp_f32_e32 v183, v183
	s_nop 0
	v_pk_fma_f32 v[102:103], v[14:15], v[180:181], v[102:103]
	v_pk_fma_f32 v[100:101], v[16:17], v[182:183], v[100:101]
	ds_read_u16 v198, v244 offset:2112
	ds_read_u16 v199, v244 offset:2240
	ds_read_u16 v200, v245 offset:2368
	ds_read_u16 v201, v245 offset:2496
	ds_read_u16 v202, v244 offset:3072
	ds_read_u16 v203, v244 offset:3200
	ds_read_u16 v204, v245 offset:3328
	ds_read_u16 v205, v245 offset:3456
	s_waitcnt lgkmcnt(8)
	v_lshlrev_b32_e32 v190, 16, v190
	v_lshlrev_b32_e32 v191, 16, v191
	v_lshlrev_b32_e32 v192, 16, v192
	v_lshlrev_b32_e32 v193, 16, v193
	v_mul_f32_e32 v190, 0xbfb8aa3b, v190
	v_mul_f32_e32 v191, 0xbfb8aa3b, v191
	v_mul_f32_e32 v192, 0xbfb8aa3b, v192
	v_mul_f32_e32 v193, 0xbfb8aa3b, v193
	v_exp_f32_e32 v190, v190
	v_exp_f32_e32 v191, v191
	v_exp_f32_e32 v192, v192
	v_exp_f32_e32 v193, v193
	v_add_f32_e32 v190, 1.0, v190
	v_add_f32_e32 v191, 1.0, v191
	v_add_f32_e32 v192, 1.0, v192
	v_add_f32_e32 v193, 1.0, v193
	v_rcp_f32_e32 v190, v190
	v_rcp_f32_e32 v191, v191
	v_rcp_f32_e32 v192, v192
	v_rcp_f32_e32 v193, v193
	s_nop 0
	v_pk_fma_f32 v[150:151], v[34:35], v[190:191], v[150:151]
	v_pk_fma_f32 v[148:149], v[36:37], v[192:193], v[148:149]
	v_lshlrev_b32_e32 v194, 16, v194
	v_lshlrev_b32_e32 v195, 16, v195
	v_lshlrev_b32_e32 v196, 16, v196
	v_lshlrev_b32_e32 v197, 16, v197
	v_mul_f32_e32 v194, 0xbfb8aa3b, v194
	v_mul_f32_e32 v195, 0xbfb8aa3b, v195
	v_mul_f32_e32 v196, 0xbfb8aa3b, v196
	v_mul_f32_e32 v197, 0xbfb8aa3b, v197
	v_exp_f32_e32 v194, v194
	v_exp_f32_e32 v195, v195
	v_exp_f32_e32 v196, v196
	v_exp_f32_e32 v197, v197
	v_add_f32_e32 v194, 1.0, v194
	v_add_f32_e32 v195, 1.0, v195
	v_add_f32_e32 v196, 1.0, v196
	v_add_f32_e32 v197, 1.0, v197
	v_rcp_f32_e32 v194, v194
	v_rcp_f32_e32 v195, v195
	v_rcp_f32_e32 v196, v196
	v_rcp_f32_e32 v197, v197
	s_nop 0
	v_pk_fma_f32 v[146:147], v[38:39], v[194:195], v[146:147]
	v_pk_fma_f32 v[142:143], v[40:41], v[196:197], v[142:143]
	s_waitcnt lgkmcnt(0)
	v_lshlrev_b32_e32 v198, 16, v198
	v_lshlrev_b32_e32 v199, 16, v199
	v_lshlrev_b32_e32 v200, 16, v200
	v_lshlrev_b32_e32 v201, 16, v201
	v_mul_f32_e32 v198, 0xbfb8aa3b, v198
	v_mul_f32_e32 v199, 0xbfb8aa3b, v199
	v_mul_f32_e32 v200, 0xbfb8aa3b, v200
	v_mul_f32_e32 v201, 0xbfb8aa3b, v201
	v_exp_f32_e32 v198, v198
	v_exp_f32_e32 v199, v199
	v_exp_f32_e32 v200, v200
	v_exp_f32_e32 v201, v201
	v_add_f32_e32 v198, 1.0, v198
	v_add_f32_e32 v199, 1.0, v199
	v_add_f32_e32 v200, 1.0, v200
	v_add_f32_e32 v201, 1.0, v201
	v_rcp_f32_e32 v198, v198
	v_rcp_f32_e32 v199, v199
	v_rcp_f32_e32 v200, v200
	v_rcp_f32_e32 v201, v201
	s_nop 0
	v_pk_fma_f32 v[140:141], v[42:43], v[198:199], v[140:141]
	v_pk_fma_f32 v[138:139], v[44:45], v[200:201], v[138:139]
	v_lshlrev_b32_e32 v202, 16, v202
	v_lshlrev_b32_e32 v203, 16, v203
	v_lshlrev_b32_e32 v204, 16, v204
	v_lshlrev_b32_e32 v205, 16, v205
	v_mul_f32_e32 v202, 0xbfb8aa3b, v202
	v_mul_f32_e32 v203, 0xbfb8aa3b, v203
	v_mul_f32_e32 v204, 0xbfb8aa3b, v204
	v_mul_f32_e32 v205, 0xbfb8aa3b, v205
	v_exp_f32_e32 v202, v202
	v_exp_f32_e32 v203, v203
	v_exp_f32_e32 v204, v204
	v_exp_f32_e32 v205, v205
	v_add_f32_e32 v202, 1.0, v202
	v_add_f32_e32 v203, 1.0, v203
	v_add_f32_e32 v204, 1.0, v204
	v_add_f32_e32 v205, 1.0, v205
	v_rcp_f32_e32 v202, v202
	v_rcp_f32_e32 v203, v203
	v_rcp_f32_e32 v204, v204
	v_rcp_f32_e32 v205, v205
	s_nop 0
	v_pk_fma_f32 v[136:137], v[46:47], v[202:203], v[136:137]
	v_pk_fma_f32 v[134:135], v[48:49], v[204:205], v[134:135]
	s_waitcnt vmcnt(0) lgkmcnt(0)
	s_barrier
	s_mov_b32 m0, vcc_lo
	ds_read_b128 v[66:69], v236 offset:32768
	global_load_lds_dwordx4 v206, s[36:37]
	s_setprio 3
	ds_read_b128 v[70:73], v240 offset:32768
	s_add_u32 m0, vcc_lo, 0x1000
	ds_read_b128 v[74:77], v240 offset:36864
	global_load_lds_dwordx4 v207, s[36:37]
	ds_read_b128 v[78:81], v236 offset:36864
	s_add_u32 m0, vcc_lo, 0x2000
	ds_read_b128 v[82:85], v237 offset:32768
	global_load_lds_dwordx4 v208, s[36:37]
	ds_read_b128 v[86:89], v241 offset:32768
	s_add_u32 m0, vcc_lo, 0x3000
	ds_read_b128 v[90:93], v241 offset:36864
	global_load_lds_dwordx4 v209, s[36:37]
	ds_read_b128 v[94:97], v237 offset:36864
	s_waitcnt lgkmcnt(6)
	v_mfma_f32_32x32x16_bf16 v[50:65], v[66:69], v[70:73], 0
	s_add_u32 m0, vcc_lo, 0x4000
	ds_read_b128 v[168:171], v238 offset:32768
	global_load_lds_dwordx4 v210, s[38:39]
	s_waitcnt lgkmcnt(5)
	v_mfma_f32_32x32x16_bf16 v[18:33], v[78:81], v[70:73], 0
	ds_read_b128 v[172:175], v242 offset:32768
	v_mfma_f32_32x32x16_bf16 v[2:17], v[78:81], v[74:77], 0
	s_add_u32 m0, vcc_lo, 0x5000
	ds_read_b128 v[176:179], v242 offset:36864
	global_load_lds_dwordx4 v211, s[38:39]
	v_mfma_f32_32x32x16_bf16 v[34:49], v[66:69], v[74:77], 0
	ds_read_b128 v[180:183], v238 offset:36864
	s_waitcnt lgkmcnt(6)
	v_mfma_f32_32x32x16_bf16 v[50:65], v[82:85], v[86:89], v[50:65]
	s_add_u32 m0, vcc_lo, 0x6000
	ds_read_b128 v[190:193], v239 offset:32768
	global_load_lds_dwordx4 v212, s[38:39]
	s_waitcnt lgkmcnt(5)
	v_mfma_f32_32x32x16_bf16 v[18:33], v[94:97], v[86:89], v[18:33]
	ds_read_b128 v[194:197], v243 offset:32768
	v_mfma_f32_32x32x16_bf16 v[2:17], v[94:97], v[90:93], v[2:17]
	s_add_u32 m0, vcc_lo, 0x7000
	ds_read_b128 v[198:201], v243 offset:36864
	global_load_lds_dwordx4 v213, s[38:39]
	v_mfma_f32_32x32x16_bf16 v[34:49], v[82:85], v[90:93], v[34:49]
	ds_read_b128 v[202:205], v239 offset:36864
	s_add_u32 s36, s36, 0x80
	s_addc_u32 s37, s37, 0
	s_add_u32 s38, s38, 0x80
	s_addc_u32 s39, s39, 0
	s_waitcnt vmcnt(0) lgkmcnt(0)
	s_barrier
	v_mfma_f32_32x32x16_bf16 v[50:65], v[168:171], v[172:175], v[50:65]
	s_add_u32 m0, vcc_lo, 0x8000
	ds_read_b128 v[66:69], v236
	global_load_lds_dwordx4 v206, s[36:37]
	s_setprio 3
	v_mfma_f32_32x32x16_bf16 v[18:33], v[180:183], v[172:175], v[18:33]
	ds_read_b128 v[70:73], v240
	v_mfma_f32_32x32x16_bf16 v[2:17], v[180:183], v[176:179], v[2:17]
	s_add_u32 m0, vcc_lo, 0x9000
	ds_read_b128 v[74:77], v240 offset:4096
	global_load_lds_dwordx4 v207, s[36:37]
	v_mfma_f32_32x32x16_bf16 v[34:49], v[168:171], v[176:179], v[34:49]
	ds_read_b128 v[78:81], v236 offset:4096
	v_mfma_f32_32x32x16_bf16 v[50:65], v[190:193], v[194:197], v[50:65]
	s_add_u32 m0, vcc_lo, 0xa000
	ds_read_b128 v[82:85], v237
	global_load_lds_dwordx4 v208, s[36:37]
	v_mfma_f32_32x32x16_bf16 v[18:33], v[202:205], v[194:197], v[18:33]
	ds_read_b128 v[86:89], v241
	v_mfma_f32_32x32x16_bf16 v[2:17], v[202:205], v[198:201], v[2:17]
	s_add_u32 m0, vcc_lo, 0xb000
	ds_read_b128 v[90:93], v241 offset:4096
	global_load_lds_dwordx4 v209, s[36:37]
	v_mfma_f32_32x32x16_bf16 v[34:49], v[190:193], v[198:201], v[34:49]
	ds_read_b128 v[94:97], v237 offset:4096
	s_waitcnt lgkmcnt(6)
	v_mfma_f32_32x32x16_bf16 v[50:65], v[66:69], v[70:73], v[50:65]
	s_add_u32 m0, vcc_lo, 0xc000
	ds_read_b128 v[168:171], v238
	global_load_lds_dwordx4 v210, s[38:39]
	s_waitcnt lgkmcnt(5)
	v_mfma_f32_32x32x16_bf16 v[18:33], v[78:81], v[70:73], v[18:33]
	ds_read_b128 v[172:175], v242
	v_mfma_f32_32x32x16_bf16 v[2:17], v[78:81], v[74:77], v[2:17]
	s_add_u32 m0, vcc_lo, 0xd000
	ds_read_b128 v[176:179], v242 offset:4096
	global_load_lds_dwordx4 v211, s[38:39]
	v_mfma_f32_32x32x16_bf16 v[34:49], v[66:69], v[74:77], v[34:49]
	ds_read_b128 v[180:183], v238 offset:4096
	s_waitcnt lgkmcnt(6)
	v_mfma_f32_32x32x16_bf16 v[50:65], v[82:85], v[86:89], v[50:65]
	s_add_u32 m0, vcc_lo, 0xe000
	ds_read_b128 v[190:193], v239
	global_load_lds_dwordx4 v212, s[38:39]
	s_waitcnt lgkmcnt(5)
	v_mfma_f32_32x32x16_bf16 v[18:33], v[94:97], v[86:89], v[18:33]
	ds_read_b128 v[194:197], v243
	v_mfma_f32_32x32x16_bf16 v[2:17], v[94:97], v[90:93], v[2:17]
	s_add_u32 m0, vcc_lo, 0xf000
	ds_read_b128 v[198:201], v243 offset:4096
	global_load_lds_dwordx4 v213, s[38:39]
	v_mfma_f32_32x32x16_bf16 v[34:49], v[82:85], v[90:93], v[34:49]
	ds_read_b128 v[202:205], v239 offset:4096
	s_add_u32 s36, s36, 0x80
	s_addc_u32 s37, s37, 0
	s_add_u32 s38, s38, 0x80
	s_addc_u32 s39, s39, 0
	s_waitcnt vmcnt(0) lgkmcnt(0)
	s_barrier
	v_mfma_f32_32x32x16_bf16 v[50:65], v[168:171], v[172:175], v[50:65]
	s_mov_b32 m0, vcc_lo
	ds_read_b128 v[66:69], v236 offset:32768
	global_load_lds_dwordx4 v206, s[36:37]
	s_setprio 3
	v_mfma_f32_32x32x16_bf16 v[18:33], v[180:183], v[172:175], v[18:33]
	ds_read_b128 v[70:73], v240 offset:32768
	v_mfma_f32_32x32x16_bf16 v[2:17], v[180:183], v[176:179], v[2:17]
	s_add_u32 m0, vcc_lo, 0x1000
	ds_read_b128 v[74:77], v240 offset:36864
	global_load_lds_dwordx4 v207, s[36:37]
	v_mfma_f32_32x32x16_bf16 v[34:49], v[168:171], v[176:179], v[34:49]
	ds_read_b128 v[78:81], v236 offset:36864
	v_mfma_f32_32x32x16_bf16 v[50:65], v[190:193], v[194:197], v[50:65]
	s_add_u32 m0, vcc_lo, 0x2000
	ds_read_b128 v[82:85], v237 offset:32768
	global_load_lds_dwordx4 v208, s[36:37]
	v_mfma_f32_32x32x16_bf16 v[18:33], v[202:205], v[194:197], v[18:33]
	ds_read_b128 v[86:89], v241 offset:32768
	v_mfma_f32_32x32x16_bf16 v[2:17], v[202:205], v[198:201], v[2:17]
	s_add_u32 m0, vcc_lo, 0x3000
	ds_read_b128 v[90:93], v241 offset:36864
	global_load_lds_dwordx4 v209, s[36:37]
	v_mfma_f32_32x32x16_bf16 v[34:49], v[190:193], v[198:201], v[34:49]
	ds_read_b128 v[94:97], v237 offset:36864
	s_waitcnt lgkmcnt(6)
	v_mfma_f32_32x32x16_bf16 v[50:65], v[66:69], v[70:73], v[50:65]
	s_add_u32 m0, vcc_lo, 0x4000
	ds_read_b128 v[168:171], v238 offset:32768
	global_load_lds_dwordx4 v210, s[38:39]
	s_waitcnt lgkmcnt(5)
	v_mfma_f32_32x32x16_bf16 v[18:33], v[78:81], v[70:73], v[18:33]
	ds_read_b128 v[172:175], v242 offset:32768
	v_mfma_f32_32x32x16_bf16 v[2:17], v[78:81], v[74:77], v[2:17]
	s_add_u32 m0, vcc_lo, 0x5000
	ds_read_b128 v[176:179], v242 offset:36864
	global_load_lds_dwordx4 v211, s[38:39]
	v_mfma_f32_32x32x16_bf16 v[34:49], v[66:69], v[74:77], v[34:49]
	ds_read_b128 v[180:183], v238 offset:36864
	s_waitcnt lgkmcnt(6)
	v_mfma_f32_32x32x16_bf16 v[50:65], v[82:85], v[86:89], v[50:65]
	s_add_u32 m0, vcc_lo, 0x6000
	ds_read_b128 v[190:193], v239 offset:32768
	global_load_lds_dwordx4 v212, s[38:39]
	s_waitcnt lgkmcnt(5)
	v_mfma_f32_32x32x16_bf16 v[18:33], v[94:97], v[86:89], v[18:33]
	ds_read_b128 v[194:197], v243 offset:32768
	v_mfma_f32_32x32x16_bf16 v[2:17], v[94:97], v[90:93], v[2:17]
	s_add_u32 m0, vcc_lo, 0x7000
	ds_read_b128 v[198:201], v243 offset:36864
	global_load_lds_dwordx4 v213, s[38:39]
	v_mfma_f32_32x32x16_bf16 v[34:49], v[82:85], v[90:93], v[34:49]
	ds_read_b128 v[202:205], v239 offset:36864
	s_add_u32 s36, s36, 0x80
	s_addc_u32 s37, s37, 0
	s_add_u32 s38, s38, 0x80
	s_addc_u32 s39, s39, 0
	s_waitcnt vmcnt(0) lgkmcnt(0)
	s_barrier
	v_mfma_f32_32x32x16_bf16 v[50:65], v[168:171], v[172:175], v[50:65]
	s_add_u32 m0, vcc_lo, 0x8000
	ds_read_b128 v[66:69], v236
	global_load_lds_dwordx4 v206, s[36:37]
	s_setprio 3
	v_mfma_f32_32x32x16_bf16 v[18:33], v[180:183], v[172:175], v[18:33]
	ds_read_b128 v[70:73], v240
	v_mfma_f32_32x32x16_bf16 v[2:17], v[180:183], v[176:179], v[2:17]
	s_add_u32 m0, vcc_lo, 0x9000
	ds_read_b128 v[74:77], v240 offset:4096
	global_load_lds_dwordx4 v207, s[36:37]
	v_mfma_f32_32x32x16_bf16 v[34:49], v[168:171], v[176:179], v[34:49]
	ds_read_b128 v[78:81], v236 offset:4096
	v_mfma_f32_32x32x16_bf16 v[50:65], v[190:193], v[194:197], v[50:65]
	s_add_u32 m0, vcc_lo, 0xa000
	ds_read_b128 v[82:85], v237
	global_load_lds_dwordx4 v208, s[36:37]
	v_mfma_f32_32x32x16_bf16 v[18:33], v[202:205], v[194:197], v[18:33]
	ds_read_b128 v[86:89], v241
	v_mfma_f32_32x32x16_bf16 v[2:17], v[202:205], v[198:201], v[2:17]
	s_add_u32 m0, vcc_lo, 0xb000
	ds_read_b128 v[90:93], v241 offset:4096
	global_load_lds_dwordx4 v209, s[36:37]
	v_mfma_f32_32x32x16_bf16 v[34:49], v[190:193], v[198:201], v[34:49]
	ds_read_b128 v[94:97], v237 offset:4096
	s_waitcnt lgkmcnt(6)
	v_mfma_f32_32x32x16_bf16 v[50:65], v[66:69], v[70:73], v[50:65]
	s_add_u32 m0, vcc_lo, 0xc000
	ds_read_b128 v[168:171], v238
	global_load_lds_dwordx4 v210, s[38:39]
	s_waitcnt lgkmcnt(5)
	v_mfma_f32_32x32x16_bf16 v[18:33], v[78:81], v[70:73], v[18:33]
	ds_read_b128 v[172:175], v242
	v_mfma_f32_32x32x16_bf16 v[2:17], v[78:81], v[74:77], v[2:17]
	s_add_u32 m0, vcc_lo, 0xd000
	ds_read_b128 v[176:179], v242 offset:4096
	global_load_lds_dwordx4 v211, s[38:39]
	v_mfma_f32_32x32x16_bf16 v[34:49], v[66:69], v[74:77], v[34:49]
	ds_read_b128 v[180:183], v238 offset:4096
	s_waitcnt lgkmcnt(6)
	v_mfma_f32_32x32x16_bf16 v[50:65], v[82:85], v[86:89], v[50:65]
	s_add_u32 m0, vcc_lo, 0xe000
	ds_read_b128 v[190:193], v239
	global_load_lds_dwordx4 v212, s[38:39]
	s_waitcnt lgkmcnt(5)
	v_mfma_f32_32x32x16_bf16 v[18:33], v[94:97], v[86:89], v[18:33]
	ds_read_b128 v[194:197], v243
	v_mfma_f32_32x32x16_bf16 v[2:17], v[94:97], v[90:93], v[2:17]
	s_add_u32 m0, vcc_lo, 0xf000
	ds_read_b128 v[198:201], v243 offset:4096
	global_load_lds_dwordx4 v213, s[38:39]
	v_mfma_f32_32x32x16_bf16 v[34:49], v[82:85], v[90:93], v[34:49]
	ds_read_b128 v[202:205], v239 offset:4096
	s_add_u32 s36, s36, 0x80
	s_addc_u32 s37, s37, 0
	s_add_u32 s38, s38, 0x80
	s_addc_u32 s39, s39, 0
	s_waitcnt vmcnt(0) lgkmcnt(0)
	s_barrier
	v_mfma_f32_32x32x16_bf16 v[50:65], v[168:171], v[172:175], v[50:65]
	s_mov_b32 m0, vcc_lo
	ds_read_b128 v[66:69], v236 offset:32768
	global_load_lds_dwordx4 v206, s[36:37]
	s_setprio 3
	v_mfma_f32_32x32x16_bf16 v[18:33], v[180:183], v[172:175], v[18:33]
	ds_read_b128 v[70:73], v240 offset:32768
	v_mfma_f32_32x32x16_bf16 v[2:17], v[180:183], v[176:179], v[2:17]
	s_add_u32 m0, vcc_lo, 0x1000
	ds_read_b128 v[74:77], v240 offset:36864
	global_load_lds_dwordx4 v207, s[36:37]
	v_mfma_f32_32x32x16_bf16 v[34:49], v[168:171], v[176:179], v[34:49]
	ds_read_b128 v[78:81], v236 offset:36864
	v_mfma_f32_32x32x16_bf16 v[50:65], v[190:193], v[194:197], v[50:65]
	s_add_u32 m0, vcc_lo, 0x2000
	ds_read_b128 v[82:85], v237 offset:32768
	global_load_lds_dwordx4 v208, s[36:37]
	v_mfma_f32_32x32x16_bf16 v[18:33], v[202:205], v[194:197], v[18:33]
	ds_read_b128 v[86:89], v241 offset:32768
	v_mfma_f32_32x32x16_bf16 v[2:17], v[202:205], v[198:201], v[2:17]
	s_add_u32 m0, vcc_lo, 0x3000
	ds_read_b128 v[90:93], v241 offset:36864
	global_load_lds_dwordx4 v209, s[36:37]
	v_mfma_f32_32x32x16_bf16 v[34:49], v[190:193], v[198:201], v[34:49]
	ds_read_b128 v[94:97], v237 offset:36864
	s_waitcnt lgkmcnt(6)
	v_mfma_f32_32x32x16_bf16 v[50:65], v[66:69], v[70:73], v[50:65]
	s_add_u32 m0, vcc_lo, 0x4000
	ds_read_b128 v[168:171], v238 offset:32768
	global_load_lds_dwordx4 v210, s[38:39]
	s_waitcnt lgkmcnt(5)
	v_mfma_f32_32x32x16_bf16 v[18:33], v[78:81], v[70:73], v[18:33]
	ds_read_b128 v[172:175], v242 offset:32768
	v_mfma_f32_32x32x16_bf16 v[2:17], v[78:81], v[74:77], v[2:17]
	s_add_u32 m0, vcc_lo, 0x5000
	ds_read_b128 v[176:179], v242 offset:36864
	global_load_lds_dwordx4 v211, s[38:39]
	v_mfma_f32_32x32x16_bf16 v[34:49], v[66:69], v[74:77], v[34:49]
	ds_read_b128 v[180:183], v238 offset:36864
	s_waitcnt lgkmcnt(6)
	v_mfma_f32_32x32x16_bf16 v[50:65], v[82:85], v[86:89], v[50:65]
	s_add_u32 m0, vcc_lo, 0x6000
	ds_read_b128 v[190:193], v239 offset:32768
	global_load_lds_dwordx4 v212, s[38:39]
	s_waitcnt lgkmcnt(5)
	v_mfma_f32_32x32x16_bf16 v[18:33], v[94:97], v[86:89], v[18:33]
	ds_read_b128 v[194:197], v243 offset:32768
	v_mfma_f32_32x32x16_bf16 v[2:17], v[94:97], v[90:93], v[2:17]
	s_add_u32 m0, vcc_lo, 0x7000
	ds_read_b128 v[198:201], v243 offset:36864
	global_load_lds_dwordx4 v213, s[38:39]
	v_mfma_f32_32x32x16_bf16 v[34:49], v[82:85], v[90:93], v[34:49]
	ds_read_b128 v[202:205], v239 offset:36864
	s_add_u32 s36, s36, 0x80
	s_addc_u32 s37, s37, 0
	s_add_u32 s38, s38, 0x80
	s_addc_u32 s39, s39, 0
	s_waitcnt vmcnt(0) lgkmcnt(0)
	s_barrier
	v_mfma_f32_32x32x16_bf16 v[50:65], v[168:171], v[172:175], v[50:65]
	s_add_u32 m0, vcc_lo, 0x8000
	ds_read_b128 v[66:69], v236
	global_load_lds_dwordx4 v206, s[36:37]
	s_setprio 3
	v_mfma_f32_32x32x16_bf16 v[18:33], v[180:183], v[172:175], v[18:33]
	ds_read_b128 v[70:73], v240
	v_mfma_f32_32x32x16_bf16 v[2:17], v[180:183], v[176:179], v[2:17]
	s_add_u32 m0, vcc_lo, 0x9000
	ds_read_b128 v[74:77], v240 offset:4096
	global_load_lds_dwordx4 v207, s[36:37]
	v_mfma_f32_32x32x16_bf16 v[34:49], v[168:171], v[176:179], v[34:49]
	ds_read_b128 v[78:81], v236 offset:4096
	v_mfma_f32_32x32x16_bf16 v[50:65], v[190:193], v[194:197], v[50:65]
	s_add_u32 m0, vcc_lo, 0xa000
	ds_read_b128 v[82:85], v237
	global_load_lds_dwordx4 v208, s[36:37]
	v_mfma_f32_32x32x16_bf16 v[18:33], v[202:205], v[194:197], v[18:33]
	ds_read_b128 v[86:89], v241
	v_mfma_f32_32x32x16_bf16 v[2:17], v[202:205], v[198:201], v[2:17]
	s_add_u32 m0, vcc_lo, 0xb000
	ds_read_b128 v[90:93], v241 offset:4096
	global_load_lds_dwordx4 v209, s[36:37]
	v_mfma_f32_32x32x16_bf16 v[34:49], v[190:193], v[198:201], v[34:49]
	ds_read_b128 v[94:97], v237 offset:4096
	s_waitcnt lgkmcnt(6)
	v_mfma_f32_32x32x16_bf16 v[50:65], v[66:69], v[70:73], v[50:65]
	s_add_u32 m0, vcc_lo, 0xc000
	ds_read_b128 v[168:171], v238
	global_load_lds_dwordx4 v210, s[38:39]
	s_waitcnt lgkmcnt(5)
	v_mfma_f32_32x32x16_bf16 v[18:33], v[78:81], v[70:73], v[18:33]
	ds_read_b128 v[172:175], v242
	v_mfma_f32_32x32x16_bf16 v[2:17], v[78:81], v[74:77], v[2:17]
	s_add_u32 m0, vcc_lo, 0xd000
	ds_read_b128 v[176:179], v242 offset:4096
	global_load_lds_dwordx4 v211, s[38:39]
	v_mfma_f32_32x32x16_bf16 v[34:49], v[66:69], v[74:77], v[34:49]
	ds_read_b128 v[180:183], v238 offset:4096
	s_waitcnt lgkmcnt(6)
	v_mfma_f32_32x32x16_bf16 v[50:65], v[82:85], v[86:89], v[50:65]
	s_add_u32 m0, vcc_lo, 0xe000
	ds_read_b128 v[190:193], v239
	global_load_lds_dwordx4 v212, s[38:39]
	s_waitcnt lgkmcnt(5)
	v_mfma_f32_32x32x16_bf16 v[18:33], v[94:97], v[86:89], v[18:33]
	ds_read_b128 v[194:197], v243
	v_mfma_f32_32x32x16_bf16 v[2:17], v[94:97], v[90:93], v[2:17]
	s_add_u32 m0, vcc_lo, 0xf000
	ds_read_b128 v[198:201], v243 offset:4096
	global_load_lds_dwordx4 v213, s[38:39]
	v_mfma_f32_32x32x16_bf16 v[34:49], v[82:85], v[90:93], v[34:49]
	ds_read_b128 v[202:205], v239 offset:4096
	s_add_u32 s36, s36, 0x80
	s_addc_u32 s37, s37, 0
	s_add_u32 s38, s38, 0x80
	s_addc_u32 s39, s39, 0
	s_waitcnt vmcnt(0) lgkmcnt(0)
	s_barrier
	v_mfma_f32_32x32x16_bf16 v[50:65], v[168:171], v[172:175], v[50:65]
	s_mov_b32 m0, vcc_lo
	ds_read_b128 v[66:69], v236 offset:32768
	global_load_lds_dwordx4 v206, s[36:37]
	s_setprio 3
	v_mfma_f32_32x32x16_bf16 v[18:33], v[180:183], v[172:175], v[18:33]
	ds_read_b128 v[70:73], v240 offset:32768
	v_mfma_f32_32x32x16_bf16 v[2:17], v[180:183], v[176:179], v[2:17]
	s_add_u32 m0, vcc_lo, 0x1000
	ds_read_b128 v[74:77], v240 offset:36864
	global_load_lds_dwordx4 v207, s[36:37]
	v_mfma_f32_32x32x16_bf16 v[34:49], v[168:171], v[176:179], v[34:49]
	ds_read_b128 v[78:81], v236 offset:36864
	v_mfma_f32_32x32x16_bf16 v[50:65], v[190:193], v[194:197], v[50:65]
	s_add_u32 m0, vcc_lo, 0x2000
	ds_read_b128 v[82:85], v237 offset:32768
	global_load_lds_dwordx4 v208, s[36:37]
	v_mfma_f32_32x32x16_bf16 v[18:33], v[202:205], v[194:197], v[18:33]
	ds_read_b128 v[86:89], v241 offset:32768
	v_mfma_f32_32x32x16_bf16 v[2:17], v[202:205], v[198:201], v[2:17]
	s_add_u32 m0, vcc_lo, 0x3000
	ds_read_b128 v[90:93], v241 offset:36864
	global_load_lds_dwordx4 v209, s[36:37]
	v_mfma_f32_32x32x16_bf16 v[34:49], v[190:193], v[198:201], v[34:49]
	ds_read_b128 v[94:97], v237 offset:36864
	s_waitcnt lgkmcnt(6)
	v_mfma_f32_32x32x16_bf16 v[50:65], v[66:69], v[70:73], v[50:65]
	s_add_u32 m0, vcc_lo, 0x4000
	ds_read_b128 v[168:171], v238 offset:32768
	global_load_lds_dwordx4 v210, s[38:39]
	s_waitcnt lgkmcnt(5)
	v_mfma_f32_32x32x16_bf16 v[18:33], v[78:81], v[70:73], v[18:33]
	ds_read_b128 v[172:175], v242 offset:32768
	v_mfma_f32_32x32x16_bf16 v[2:17], v[78:81], v[74:77], v[2:17]
	s_add_u32 m0, vcc_lo, 0x5000
	ds_read_b128 v[176:179], v242 offset:36864
	global_load_lds_dwordx4 v211, s[38:39]
	v_mfma_f32_32x32x16_bf16 v[34:49], v[66:69], v[74:77], v[34:49]
	ds_read_b128 v[180:183], v238 offset:36864
	s_waitcnt lgkmcnt(6)
	v_mfma_f32_32x32x16_bf16 v[50:65], v[82:85], v[86:89], v[50:65]
	s_add_u32 m0, vcc_lo, 0x6000
	ds_read_b128 v[190:193], v239 offset:32768
	global_load_lds_dwordx4 v212, s[38:39]
	s_waitcnt lgkmcnt(5)
	v_mfma_f32_32x32x16_bf16 v[18:33], v[94:97], v[86:89], v[18:33]
	ds_read_b128 v[194:197], v243 offset:32768
	v_mfma_f32_32x32x16_bf16 v[2:17], v[94:97], v[90:93], v[2:17]
	s_add_u32 m0, vcc_lo, 0x7000
	ds_read_b128 v[198:201], v243 offset:36864
	global_load_lds_dwordx4 v213, s[38:39]
	v_mfma_f32_32x32x16_bf16 v[34:49], v[82:85], v[90:93], v[34:49]
	ds_read_b128 v[202:205], v239 offset:36864
	s_add_u32 s38, s38, 0x80
	s_addc_u32 s39, s39, 0
	s_add_u32 s36, s50, 0x9425000
	s_addc_u32 s37, s51, 0
	s_waitcnt vmcnt(0) lgkmcnt(0)
	s_barrier
	v_mfma_f32_32x32x16_bf16 v[50:65], v[168:171], v[172:175], v[50:65]
	s_add_u32 m0, vcc_lo, 0x8000
	ds_read_b128 v[66:69], v236
	global_load_lds_dwordx4 v222, s[40:41]
	s_setprio 3
	v_mfma_f32_32x32x16_bf16 v[18:33], v[180:183], v[172:175], v[18:33]
	ds_read_b128 v[70:73], v240
	v_mfma_f32_32x32x16_bf16 v[2:17], v[180:183], v[176:179], v[2:17]
	s_add_u32 m0, vcc_lo, 0x9000
	ds_read_b128 v[74:77], v240 offset:4096
	global_load_lds_dwordx4 v223, s[40:41]
	v_mfma_f32_32x32x16_bf16 v[34:49], v[168:171], v[176:179], v[34:49]
	ds_read_b128 v[78:81], v236 offset:4096
	v_mfma_f32_32x32x16_bf16 v[50:65], v[190:193], v[194:197], v[50:65]
	s_add_u32 m0, vcc_lo, 0xa000
	ds_read_b128 v[82:85], v237
	global_load_lds_dwordx4 v224, s[40:41]
	v_mfma_f32_32x32x16_bf16 v[18:33], v[202:205], v[194:197], v[18:33]
	ds_read_b128 v[86:89], v241
	v_mfma_f32_32x32x16_bf16 v[2:17], v[202:205], v[198:201], v[2:17]
	s_add_u32 m0, vcc_lo, 0xb000
	ds_read_b128 v[90:93], v241 offset:4096
	global_load_lds_dwordx4 v225, s[40:41]
	v_mfma_f32_32x32x16_bf16 v[34:49], v[190:193], v[198:201], v[34:49]
	ds_read_b128 v[94:97], v237 offset:4096
	s_waitcnt lgkmcnt(6)
	v_mfma_f32_32x32x16_bf16 v[50:65], v[66:69], v[70:73], v[50:65]
	s_add_u32 m0, vcc_lo, 0xc000
	ds_read_b128 v[168:171], v238
	global_load_lds_dwordx4 v222, s[42:43]
	s_waitcnt lgkmcnt(5)
	v_mfma_f32_32x32x16_bf16 v[18:33], v[78:81], v[70:73], v[18:33]
	ds_read_b128 v[172:175], v242
	v_mfma_f32_32x32x16_bf16 v[2:17], v[78:81], v[74:77], v[2:17]
	s_add_u32 m0, vcc_lo, 0xd000
	ds_read_b128 v[176:179], v242 offset:4096
	global_load_lds_dwordx4 v223, s[42:43]
	v_mfma_f32_32x32x16_bf16 v[34:49], v[66:69], v[74:77], v[34:49]
	ds_read_b128 v[180:183], v238 offset:4096
	s_waitcnt lgkmcnt(6)
	v_mfma_f32_32x32x16_bf16 v[50:65], v[82:85], v[86:89], v[50:65]
	s_add_u32 m0, vcc_lo, 0xe000
	ds_read_b128 v[190:193], v239
	global_load_lds_dwordx4 v224, s[42:43]
	s_waitcnt lgkmcnt(5)
	v_mfma_f32_32x32x16_bf16 v[18:33], v[94:97], v[86:89], v[18:33]
	ds_read_b128 v[194:197], v243
	v_mfma_f32_32x32x16_bf16 v[2:17], v[94:97], v[90:93], v[2:17]
	s_add_u32 m0, vcc_lo, 0xf000
	ds_read_b128 v[198:201], v243 offset:4096
	global_load_lds_dwordx4 v225, s[42:43]
	v_mfma_f32_32x32x16_bf16 v[34:49], v[82:85], v[90:93], v[34:49]
	ds_read_b128 v[202:205], v239 offset:4096
	s_add_u32 s40, s40, 0x800
	s_addc_u32 s41, s41, 0
	s_add_u32 s42, s42, 0x800
	s_addc_u32 s43, s43, 0
	s_waitcnt vmcnt(0) lgkmcnt(0)
	s_barrier
	s_mov_b32 m0, vcc_lo
	v_mfma_f32_32x32x16_bf16 v[50:65], v[168:171], v[172:175], v[50:65]
	global_load_lds_dwordx4 v206, s[36:37]
	s_add_u32 m0, vcc_lo, 0x1000
	v_mfma_f32_32x32x16_bf16 v[18:33], v[180:183], v[172:175], v[18:33]
	global_load_lds_dwordx4 v207, s[36:37]
	s_add_u32 m0, vcc_lo, 0x2000
	v_mfma_f32_32x32x16_bf16 v[2:17], v[180:183], v[176:179], v[2:17]
	global_load_lds_dwordx4 v208, s[36:37]
	s_add_u32 m0, vcc_lo, 0x3000
	v_mfma_f32_32x32x16_bf16 v[34:49], v[168:171], v[176:179], v[34:49]
	global_load_lds_dwordx4 v209, s[36:37]
	s_add_u32 m0, vcc_lo, 0x4000
	v_mfma_f32_32x32x16_bf16 v[50:65], v[190:193], v[194:197], v[50:65]
	global_load_lds_dwordx4 v210, s[38:39]
	s_add_u32 m0, vcc_lo, 0x5000
	v_mfma_f32_32x32x16_bf16 v[18:33], v[202:205], v[194:197], v[18:33]
	global_load_lds_dwordx4 v211, s[38:39]
	s_add_u32 m0, vcc_lo, 0x6000
	v_mfma_f32_32x32x16_bf16 v[2:17], v[202:205], v[198:201], v[2:17]
	global_load_lds_dwordx4 v212, s[38:39]
	s_add_u32 m0, vcc_lo, 0x7000
	v_mfma_f32_32x32x16_bf16 v[34:49], v[190:193], v[198:201], v[34:49]
	global_load_lds_dwordx4 v213, s[38:39]
	s_add_u32 s36, s36, 0x80
	s_addc_u32 s37, s37, 0
	s_add_u32 s38, s38, 0x80
	s_addc_u32 s39, s39, 0
	s_setprio 0
	ds_read_u16 v66, v244 offset:32768
	ds_read_u16 v67, v244 offset:32896
	ds_read_u16 v68, v245 offset:33024
	ds_read_u16 v69, v245 offset:33152
	ds_read_u16 v70, v244 offset:33856
	ds_read_u16 v71, v244 offset:33984
	ds_read_u16 v72, v245 offset:34112
	ds_read_u16 v73, v245 offset:34240
	s_nop 7
	s_nop 7
	ds_read_u16 v74, v244 offset:34816
	ds_read_u16 v75, v244 offset:34944
	ds_read_u16 v76, v245 offset:35072
	ds_read_u16 v77, v245 offset:35200
	ds_read_u16 v78, v244 offset:35904
	ds_read_u16 v79, v244 offset:36032
	ds_read_u16 v80, v245 offset:36160
	ds_read_u16 v81, v245 offset:36288
	s_waitcnt lgkmcnt(8)
	v_lshlrev_b32_e32 v66, 16, v66
	v_lshlrev_b32_e32 v67, 16, v67
	v_lshlrev_b32_e32 v68, 16, v68
	v_lshlrev_b32_e32 v69, 16, v69
	v_mul_f32_e32 v66, 0xbfb8aa3b, v66
	v_mul_f32_e32 v67, 0xbfb8aa3b, v67
	v_mul_f32_e32 v68, 0xbfb8aa3b, v68
	v_mul_f32_e32 v69, 0xbfb8aa3b, v69
	v_exp_f32_e32 v66, v66
	v_exp_f32_e32 v67, v67
	v_exp_f32_e32 v68, v68
	v_exp_f32_e32 v69, v69
	v_add_f32_e32 v66, 1.0, v66
	v_add_f32_e32 v67, 1.0, v67
	v_add_f32_e32 v68, 1.0, v68
	v_add_f32_e32 v69, 1.0, v69
	v_rcp_f32_e32 v66, v66
	v_rcp_f32_e32 v67, v67
	v_rcp_f32_e32 v68, v68
	v_rcp_f32_e32 v69, v69
	s_nop 0
	v_pk_fma_f32 v[166:167], v[50:51], v[66:67], v[166:167]
	v_pk_fma_f32 v[164:165], v[52:53], v[68:69], v[164:165]
	v_lshlrev_b32_e32 v70, 16, v70
	v_lshlrev_b32_e32 v71, 16, v71
	v_lshlrev_b32_e32 v72, 16, v72
	v_lshlrev_b32_e32 v73, 16, v73
	v_mul_f32_e32 v70, 0xbfb8aa3b, v70
	v_mul_f32_e32 v71, 0xbfb8aa3b, v71
	v_mul_f32_e32 v72, 0xbfb8aa3b, v72
	v_mul_f32_e32 v73, 0xbfb8aa3b, v73
	v_exp_f32_e32 v70, v70
	v_exp_f32_e32 v71, v71
	v_exp_f32_e32 v72, v72
	v_exp_f32_e32 v73, v73
	v_add_f32_e32 v70, 1.0, v70
	v_add_f32_e32 v71, 1.0, v71
	v_add_f32_e32 v72, 1.0, v72
	v_add_f32_e32 v73, 1.0, v73
	v_rcp_f32_e32 v70, v70
	v_rcp_f32_e32 v71, v71
	v_rcp_f32_e32 v72, v72
	v_rcp_f32_e32 v73, v73
	s_nop 0
	v_pk_fma_f32 v[162:163], v[54:55], v[70:71], v[162:163]
	v_pk_fma_f32 v[160:161], v[56:57], v[72:73], v[160:161]
	ds_read_u16 v82, v244 offset:36864
	ds_read_u16 v83, v244 offset:36992
	ds_read_u16 v84, v245 offset:37120
	ds_read_u16 v85, v245 offset:37248
	ds_read_u16 v86, v244 offset:37952
	ds_read_u16 v87, v244 offset:38080
	ds_read_u16 v88, v245 offset:38208
	ds_read_u16 v89, v245 offset:38336
	s_waitcnt lgkmcnt(8)
	v_lshlrev_b32_e32 v74, 16, v74
	v_lshlrev_b32_e32 v75, 16, v75
	v_lshlrev_b32_e32 v76, 16, v76
	v_lshlrev_b32_e32 v77, 16, v77
	v_mul_f32_e32 v74, 0xbfb8aa3b, v74
	v_mul_f32_e32 v75, 0xbfb8aa3b, v75
	v_mul_f32_e32 v76, 0xbfb8aa3b, v76
	v_mul_f32_e32 v77, 0xbfb8aa3b, v77
	v_exp_f32_e32 v74, v74
	v_exp_f32_e32 v75, v75
	v_exp_f32_e32 v76, v76
	v_exp_f32_e32 v77, v77
	v_add_f32_e32 v74, 1.0, v74
	v_add_f32_e32 v75, 1.0, v75
	v_add_f32_e32 v76, 1.0, v76
	v_add_f32_e32 v77, 1.0, v77
	v_rcp_f32_e32 v74, v74
	v_rcp_f32_e32 v75, v75
	v_rcp_f32_e32 v76, v76
	v_rcp_f32_e32 v77, v77
	s_nop 0
	v_pk_fma_f32 v[158:159], v[58:59], v[74:75], v[158:159]
	v_pk_fma_f32 v[156:157], v[60:61], v[76:77], v[156:157]
	v_lshlrev_b32_e32 v78, 16, v78
	v_lshlrev_b32_e32 v79, 16, v79
	v_lshlrev_b32_e32 v80, 16, v80
	v_lshlrev_b32_e32 v81, 16, v81
	v_mul_f32_e32 v78, 0xbfb8aa3b, v78
	v_mul_f32_e32 v79, 0xbfb8aa3b, v79
	v_mul_f32_e32 v80, 0xbfb8aa3b, v80
	v_mul_f32_e32 v81, 0xbfb8aa3b, v81
	v_exp_f32_e32 v78, v78
	v_exp_f32_e32 v79, v79
	v_exp_f32_e32 v80, v80
	v_exp_f32_e32 v81, v81
	v_add_f32_e32 v78, 1.0, v78
	v_add_f32_e32 v79, 1.0, v79
	v_add_f32_e32 v80, 1.0, v80
	v_add_f32_e32 v81, 1.0, v81
	v_rcp_f32_e32 v78, v78
	v_rcp_f32_e32 v79, v79
	v_rcp_f32_e32 v80, v80
	v_rcp_f32_e32 v81, v81
	s_nop 0
	v_pk_fma_f32 v[154:155], v[62:63], v[78:79], v[154:155]
	v_pk_fma_f32 v[152:153], v[64:65], v[80:81], v[152:153]
	ds_read_u16 v90, v244 offset:38912
	ds_read_u16 v91, v244 offset:39040
	ds_read_u16 v92, v245 offset:39168
	ds_read_u16 v93, v245 offset:39296
	ds_read_u16 v94, v244 offset:40000
	ds_read_u16 v95, v244 offset:40128
	ds_read_u16 v96, v245 offset:40256
	ds_read_u16 v97, v245 offset:40384
	s_waitcnt lgkmcnt(8)
	v_lshlrev_b32_e32 v82, 16, v82
	v_lshlrev_b32_e32 v83, 16, v83
	v_lshlrev_b32_e32 v84, 16, v84
	v_lshlrev_b32_e32 v85, 16, v85
	v_mul_f32_e32 v82, 0xbfb8aa3b, v82
	v_mul_f32_e32 v83, 0xbfb8aa3b, v83
	v_mul_f32_e32 v84, 0xbfb8aa3b, v84
	v_mul_f32_e32 v85, 0xbfb8aa3b, v85
	v_exp_f32_e32 v82, v82
	v_exp_f32_e32 v83, v83
	v_exp_f32_e32 v84, v84
	v_exp_f32_e32 v85, v85
	v_add_f32_e32 v82, 1.0, v82
	v_add_f32_e32 v83, 1.0, v83
	v_add_f32_e32 v84, 1.0, v84
	v_add_f32_e32 v85, 1.0, v85
	v_rcp_f32_e32 v82, v82
	v_rcp_f32_e32 v83, v83
	v_rcp_f32_e32 v84, v84
	v_rcp_f32_e32 v85, v85
	s_nop 0
	v_pk_fma_f32 v[130:131], v[18:19], v[82:83], v[130:131]
	v_pk_fma_f32 v[128:129], v[20:21], v[84:85], v[128:129]
	v_lshlrev_b32_e32 v86, 16, v86
	v_lshlrev_b32_e32 v87, 16, v87
	v_lshlrev_b32_e32 v88, 16, v88
	v_lshlrev_b32_e32 v89, 16, v89
	v_mul_f32_e32 v86, 0xbfb8aa3b, v86
	v_mul_f32_e32 v87, 0xbfb8aa3b, v87
	v_mul_f32_e32 v88, 0xbfb8aa3b, v88
	v_mul_f32_e32 v89, 0xbfb8aa3b, v89
	v_exp_f32_e32 v86, v86
	v_exp_f32_e32 v87, v87
	v_exp_f32_e32 v88, v88
	v_exp_f32_e32 v89, v89
	v_add_f32_e32 v86, 1.0, v86
	v_add_f32_e32 v87, 1.0, v87
	v_add_f32_e32 v88, 1.0, v88
	v_add_f32_e32 v89, 1.0, v89
	v_rcp_f32_e32 v86, v86
	v_rcp_f32_e32 v87, v87
	v_rcp_f32_e32 v88, v88
	v_rcp_f32_e32 v89, v89
	s_nop 0
	v_pk_fma_f32 v[126:127], v[22:23], v[86:87], v[126:127]
	v_pk_fma_f32 v[124:125], v[24:25], v[88:89], v[124:125]
	ds_read_u16 v168, v244 offset:36928
	ds_read_u16 v169, v244 offset:37056
	ds_read_u16 v170, v245 offset:37184
	ds_read_u16 v171, v245 offset:37312
	ds_read_u16 v172, v244 offset:37888
	ds_read_u16 v173, v244 offset:38016
	ds_read_u16 v174, v245 offset:38144
	ds_read_u16 v175, v245 offset:38272
	s_waitcnt lgkmcnt(8)
	v_lshlrev_b32_e32 v90, 16, v90
	v_lshlrev_b32_e32 v91, 16, v91
	v_lshlrev_b32_e32 v92, 16, v92
	v_lshlrev_b32_e32 v93, 16, v93
	v_mul_f32_e32 v90, 0xbfb8aa3b, v90
	v_mul_f32_e32 v91, 0xbfb8aa3b, v91
	v_mul_f32_e32 v92, 0xbfb8aa3b, v92
	v_mul_f32_e32 v93, 0xbfb8aa3b, v93
	v_exp_f32_e32 v90, v90
	v_exp_f32_e32 v91, v91
	v_exp_f32_e32 v92, v92
	v_exp_f32_e32 v93, v93
	v_add_f32_e32 v90, 1.0, v90
	v_add_f32_e32 v91, 1.0, v91
	v_add_f32_e32 v92, 1.0, v92
	v_add_f32_e32 v93, 1.0, v93
	v_rcp_f32_e32 v90, v90
	v_rcp_f32_e32 v91, v91
	v_rcp_f32_e32 v92, v92
	v_rcp_f32_e32 v93, v93
	s_nop 0
	v_pk_fma_f32 v[122:123], v[26:27], v[90:91], v[122:123]
	v_pk_fma_f32 v[120:121], v[28:29], v[92:93], v[120:121]
	v_lshlrev_b32_e32 v94, 16, v94
	v_lshlrev_b32_e32 v95, 16, v95
	v_lshlrev_b32_e32 v96, 16, v96
	v_lshlrev_b32_e32 v97, 16, v97
	v_mul_f32_e32 v94, 0xbfb8aa3b, v94
	v_mul_f32_e32 v95, 0xbfb8aa3b, v95
	v_mul_f32_e32 v96, 0xbfb8aa3b, v96
	v_mul_f32_e32 v97, 0xbfb8aa3b, v97
	v_exp_f32_e32 v94, v94
	v_exp_f32_e32 v95, v95
	v_exp_f32_e32 v96, v96
	v_exp_f32_e32 v97, v97
	v_add_f32_e32 v94, 1.0, v94
	v_add_f32_e32 v95, 1.0, v95
	v_add_f32_e32 v96, 1.0, v96
	v_add_f32_e32 v97, 1.0, v97
	v_rcp_f32_e32 v94, v94
	v_rcp_f32_e32 v95, v95
	v_rcp_f32_e32 v96, v96
	v_rcp_f32_e32 v97, v97
	s_nop 0
	v_pk_fma_f32 v[118:119], v[30:31], v[94:95], v[118:119]
	v_pk_fma_f32 v[116:117], v[32:33], v[96:97], v[116:117]
	ds_read_u16 v176, v244 offset:38976
	ds_read_u16 v177, v244 offset:39104
	ds_read_u16 v178, v245 offset:39232
	ds_read_u16 v179, v245 offset:39360
	ds_read_u16 v180, v244 offset:39936
	ds_read_u16 v181, v244 offset:40064
	ds_read_u16 v182, v245 offset:40192
	ds_read_u16 v183, v245 offset:40320
	s_waitcnt lgkmcnt(8)
	v_lshlrev_b32_e32 v168, 16, v168
	v_lshlrev_b32_e32 v169, 16, v169
	v_lshlrev_b32_e32 v170, 16, v170
	v_lshlrev_b32_e32 v171, 16, v171
	v_mul_f32_e32 v168, 0xbfb8aa3b, v168
	v_mul_f32_e32 v169, 0xbfb8aa3b, v169
	v_mul_f32_e32 v170, 0xbfb8aa3b, v170
	v_mul_f32_e32 v171, 0xbfb8aa3b, v171
	v_exp_f32_e32 v168, v168
	v_exp_f32_e32 v169, v169
	v_exp_f32_e32 v170, v170
	v_exp_f32_e32 v171, v171
	v_add_f32_e32 v168, 1.0, v168
	v_add_f32_e32 v169, 1.0, v169
	v_add_f32_e32 v170, 1.0, v170
	v_add_f32_e32 v171, 1.0, v171
	v_rcp_f32_e32 v168, v168
	v_rcp_f32_e32 v169, v169
	v_rcp_f32_e32 v170, v170
	v_rcp_f32_e32 v171, v171
	s_nop 0
	v_pk_fma_f32 v[114:115], v[2:3], v[168:169], v[114:115]
	v_pk_fma_f32 v[112:113], v[4:5], v[170:171], v[112:113]
	v_lshlrev_b32_e32 v172, 16, v172
	v_lshlrev_b32_e32 v173, 16, v173
	v_lshlrev_b32_e32 v174, 16, v174
	v_lshlrev_b32_e32 v175, 16, v175
	v_mul_f32_e32 v172, 0xbfb8aa3b, v172
	v_mul_f32_e32 v173, 0xbfb8aa3b, v173
	v_mul_f32_e32 v174, 0xbfb8aa3b, v174
	v_mul_f32_e32 v175, 0xbfb8aa3b, v175
	v_exp_f32_e32 v172, v172
	v_exp_f32_e32 v173, v173
	v_exp_f32_e32 v174, v174
	v_exp_f32_e32 v175, v175
	v_add_f32_e32 v172, 1.0, v172
	v_add_f32_e32 v173, 1.0, v173
	v_add_f32_e32 v174, 1.0, v174
	v_add_f32_e32 v175, 1.0, v175
	v_rcp_f32_e32 v172, v172
	v_rcp_f32_e32 v173, v173
	v_rcp_f32_e32 v174, v174
	v_rcp_f32_e32 v175, v175
	s_nop 0
	v_pk_fma_f32 v[110:111], v[6:7], v[172:173], v[110:111]
	v_pk_fma_f32 v[108:109], v[8:9], v[174:175], v[108:109]
	ds_read_u16 v190, v244 offset:32832
	ds_read_u16 v191, v244 offset:32960
	ds_read_u16 v192, v245 offset:33088
	ds_read_u16 v193, v245 offset:33216
	ds_read_u16 v194, v244 offset:33792
	ds_read_u16 v195, v244 offset:33920
	ds_read_u16 v196, v245 offset:34048
	ds_read_u16 v197, v245 offset:34176
	s_waitcnt lgkmcnt(8)
	v_lshlrev_b32_e32 v176, 16, v176
	v_lshlrev_b32_e32 v177, 16, v177
	v_lshlrev_b32_e32 v178, 16, v178
	v_lshlrev_b32_e32 v179, 16, v179
	v_mul_f32_e32 v176, 0xbfb8aa3b, v176
	v_mul_f32_e32 v177, 0xbfb8aa3b, v177
	v_mul_f32_e32 v178, 0xbfb8aa3b, v178
	v_mul_f32_e32 v179, 0xbfb8aa3b, v179
	v_exp_f32_e32 v176, v176
	v_exp_f32_e32 v177, v177
	v_exp_f32_e32 v178, v178
	v_exp_f32_e32 v179, v179
	v_add_f32_e32 v176, 1.0, v176
	v_add_f32_e32 v177, 1.0, v177
	v_add_f32_e32 v178, 1.0, v178
	v_add_f32_e32 v179, 1.0, v179
	v_rcp_f32_e32 v176, v176
	v_rcp_f32_e32 v177, v177
	v_rcp_f32_e32 v178, v178
	v_rcp_f32_e32 v179, v179
	s_nop 0
	v_pk_fma_f32 v[106:107], v[10:11], v[176:177], v[106:107]
	v_pk_fma_f32 v[104:105], v[12:13], v[178:179], v[104:105]
	v_lshlrev_b32_e32 v180, 16, v180
	v_lshlrev_b32_e32 v181, 16, v181
	v_lshlrev_b32_e32 v182, 16, v182
	v_lshlrev_b32_e32 v183, 16, v183
	v_mul_f32_e32 v180, 0xbfb8aa3b, v180
	v_mul_f32_e32 v181, 0xbfb8aa3b, v181
	v_mul_f32_e32 v182, 0xbfb8aa3b, v182
	v_mul_f32_e32 v183, 0xbfb8aa3b, v183
	v_exp_f32_e32 v180, v180
	v_exp_f32_e32 v181, v181
	v_exp_f32_e32 v182, v182
	v_exp_f32_e32 v183, v183
	v_add_f32_e32 v180, 1.0, v180
	v_add_f32_e32 v181, 1.0, v181
	v_add_f32_e32 v182, 1.0, v182
	v_add_f32_e32 v183, 1.0, v183
	v_rcp_f32_e32 v180, v180
	v_rcp_f32_e32 v181, v181
	v_rcp_f32_e32 v182, v182
	v_rcp_f32_e32 v183, v183
	s_nop 0
	v_pk_fma_f32 v[102:103], v[14:15], v[180:181], v[102:103]
	v_pk_fma_f32 v[100:101], v[16:17], v[182:183], v[100:101]
	ds_read_u16 v198, v244 offset:34880
	ds_read_u16 v199, v244 offset:35008
	ds_read_u16 v200, v245 offset:35136
	ds_read_u16 v201, v245 offset:35264
	ds_read_u16 v202, v244 offset:35840
	ds_read_u16 v203, v244 offset:35968
	ds_read_u16 v204, v245 offset:36096
	ds_read_u16 v205, v245 offset:36224
	s_waitcnt lgkmcnt(8)
	v_lshlrev_b32_e32 v190, 16, v190
	v_lshlrev_b32_e32 v191, 16, v191
	v_lshlrev_b32_e32 v192, 16, v192
	v_lshlrev_b32_e32 v193, 16, v193
	v_mul_f32_e32 v190, 0xbfb8aa3b, v190
	v_mul_f32_e32 v191, 0xbfb8aa3b, v191
	v_mul_f32_e32 v192, 0xbfb8aa3b, v192
	v_mul_f32_e32 v193, 0xbfb8aa3b, v193
	v_exp_f32_e32 v190, v190
	v_exp_f32_e32 v191, v191
	v_exp_f32_e32 v192, v192
	v_exp_f32_e32 v193, v193
	v_add_f32_e32 v190, 1.0, v190
	v_add_f32_e32 v191, 1.0, v191
	v_add_f32_e32 v192, 1.0, v192
	v_add_f32_e32 v193, 1.0, v193
	v_rcp_f32_e32 v190, v190
	v_rcp_f32_e32 v191, v191
	v_rcp_f32_e32 v192, v192
	v_rcp_f32_e32 v193, v193
	s_nop 0
	v_pk_fma_f32 v[150:151], v[34:35], v[190:191], v[150:151]
	v_pk_fma_f32 v[148:149], v[36:37], v[192:193], v[148:149]
	v_lshlrev_b32_e32 v194, 16, v194
	v_lshlrev_b32_e32 v195, 16, v195
	v_lshlrev_b32_e32 v196, 16, v196
	v_lshlrev_b32_e32 v197, 16, v197
	v_mul_f32_e32 v194, 0xbfb8aa3b, v194
	v_mul_f32_e32 v195, 0xbfb8aa3b, v195
	v_mul_f32_e32 v196, 0xbfb8aa3b, v196
	v_mul_f32_e32 v197, 0xbfb8aa3b, v197
	v_exp_f32_e32 v194, v194
	v_exp_f32_e32 v195, v195
	v_exp_f32_e32 v196, v196
	v_exp_f32_e32 v197, v197
	v_add_f32_e32 v194, 1.0, v194
	v_add_f32_e32 v195, 1.0, v195
	v_add_f32_e32 v196, 1.0, v196
	v_add_f32_e32 v197, 1.0, v197
	v_rcp_f32_e32 v194, v194
	v_rcp_f32_e32 v195, v195
	v_rcp_f32_e32 v196, v196
	v_rcp_f32_e32 v197, v197
	s_nop 0
	v_pk_fma_f32 v[146:147], v[38:39], v[194:195], v[146:147]
	v_pk_fma_f32 v[142:143], v[40:41], v[196:197], v[142:143]
	s_waitcnt lgkmcnt(0)
	v_lshlrev_b32_e32 v198, 16, v198
	v_lshlrev_b32_e32 v199, 16, v199
	v_lshlrev_b32_e32 v200, 16, v200
	v_lshlrev_b32_e32 v201, 16, v201
	v_mul_f32_e32 v198, 0xbfb8aa3b, v198
	v_mul_f32_e32 v199, 0xbfb8aa3b, v199
	v_mul_f32_e32 v200, 0xbfb8aa3b, v200
	v_mul_f32_e32 v201, 0xbfb8aa3b, v201
	v_exp_f32_e32 v198, v198
	v_exp_f32_e32 v199, v199
	v_exp_f32_e32 v200, v200
	v_exp_f32_e32 v201, v201
	v_add_f32_e32 v198, 1.0, v198
	v_add_f32_e32 v199, 1.0, v199
	v_add_f32_e32 v200, 1.0, v200
	v_add_f32_e32 v201, 1.0, v201
	v_rcp_f32_e32 v198, v198
	v_rcp_f32_e32 v199, v199
	v_rcp_f32_e32 v200, v200
	v_rcp_f32_e32 v201, v201
	s_nop 0
	v_pk_fma_f32 v[140:141], v[42:43], v[198:199], v[140:141]
	v_pk_fma_f32 v[138:139], v[44:45], v[200:201], v[138:139]
	v_lshlrev_b32_e32 v202, 16, v202
	v_lshlrev_b32_e32 v203, 16, v203
	v_lshlrev_b32_e32 v204, 16, v204
	v_lshlrev_b32_e32 v205, 16, v205
	v_mul_f32_e32 v202, 0xbfb8aa3b, v202
	v_mul_f32_e32 v203, 0xbfb8aa3b, v203
	v_mul_f32_e32 v204, 0xbfb8aa3b, v204
	v_mul_f32_e32 v205, 0xbfb8aa3b, v205
	v_exp_f32_e32 v202, v202
	v_exp_f32_e32 v203, v203
	v_exp_f32_e32 v204, v204
	v_exp_f32_e32 v205, v205
	v_add_f32_e32 v202, 1.0, v202
	v_add_f32_e32 v203, 1.0, v203
	v_add_f32_e32 v204, 1.0, v204
	v_add_f32_e32 v205, 1.0, v205
	v_rcp_f32_e32 v202, v202
	v_rcp_f32_e32 v203, v203
	v_rcp_f32_e32 v204, v204
	v_rcp_f32_e32 v205, v205
	s_nop 0
	v_pk_fma_f32 v[136:137], v[46:47], v[202:203], v[136:137]
	v_pk_fma_f32 v[134:135], v[48:49], v[204:205], v[134:135]
	s_waitcnt vmcnt(0) lgkmcnt(0)
	s_barrier
	s_add_u32 m0, vcc_lo, 0x8000
	ds_read_b128 v[66:69], v236
	global_load_lds_dwordx4 v206, s[36:37]
	s_setprio 3
	ds_read_b128 v[70:73], v240
	s_add_u32 m0, vcc_lo, 0x9000
	ds_read_b128 v[74:77], v240 offset:4096
	global_load_lds_dwordx4 v207, s[36:37]
	ds_read_b128 v[78:81], v236 offset:4096
	s_add_u32 m0, vcc_lo, 0xa000
	ds_read_b128 v[82:85], v237
	global_load_lds_dwordx4 v208, s[36:37]
	ds_read_b128 v[86:89], v241
	s_add_u32 m0, vcc_lo, 0xb000
	ds_read_b128 v[90:93], v241 offset:4096
	global_load_lds_dwordx4 v209, s[36:37]
	ds_read_b128 v[94:97], v237 offset:4096
	s_waitcnt lgkmcnt(6)
	v_mfma_f32_32x32x16_bf16 v[50:65], v[66:69], v[70:73], 0
	s_add_u32 m0, vcc_lo, 0xc000
	ds_read_b128 v[168:171], v238
	global_load_lds_dwordx4 v210, s[38:39]
	s_waitcnt lgkmcnt(5)
	v_mfma_f32_32x32x16_bf16 v[18:33], v[78:81], v[70:73], 0
	ds_read_b128 v[172:175], v242
	v_mfma_f32_32x32x16_bf16 v[2:17], v[78:81], v[74:77], 0
	s_add_u32 m0, vcc_lo, 0xd000
	ds_read_b128 v[176:179], v242 offset:4096
	global_load_lds_dwordx4 v211, s[38:39]
	v_mfma_f32_32x32x16_bf16 v[34:49], v[66:69], v[74:77], 0
	ds_read_b128 v[180:183], v238 offset:4096
	s_waitcnt lgkmcnt(6)
	v_mfma_f32_32x32x16_bf16 v[50:65], v[82:85], v[86:89], v[50:65]
	s_add_u32 m0, vcc_lo, 0xe000
	ds_read_b128 v[190:193], v239
	global_load_lds_dwordx4 v212, s[38:39]
	s_waitcnt lgkmcnt(5)
	v_mfma_f32_32x32x16_bf16 v[18:33], v[94:97], v[86:89], v[18:33]
	ds_read_b128 v[194:197], v243
	v_mfma_f32_32x32x16_bf16 v[2:17], v[94:97], v[90:93], v[2:17]
	s_add_u32 m0, vcc_lo, 0xf000
	ds_read_b128 v[198:201], v243 offset:4096
	global_load_lds_dwordx4 v213, s[38:39]
	v_mfma_f32_32x32x16_bf16 v[34:49], v[82:85], v[90:93], v[34:49]
	ds_read_b128 v[202:205], v239 offset:4096
	s_add_u32 s36, s36, 0x80
	s_addc_u32 s37, s37, 0
	s_add_u32 s38, s38, 0x80
	s_addc_u32 s39, s39, 0
	s_waitcnt vmcnt(0) lgkmcnt(0)
	s_barrier
	v_mfma_f32_32x32x16_bf16 v[50:65], v[168:171], v[172:175], v[50:65]
	s_mov_b32 m0, vcc_lo
	ds_read_b128 v[66:69], v236 offset:32768
	global_load_lds_dwordx4 v206, s[36:37]
	s_setprio 3
	v_mfma_f32_32x32x16_bf16 v[18:33], v[180:183], v[172:175], v[18:33]
	ds_read_b128 v[70:73], v240 offset:32768
	v_mfma_f32_32x32x16_bf16 v[2:17], v[180:183], v[176:179], v[2:17]
	s_add_u32 m0, vcc_lo, 0x1000
	ds_read_b128 v[74:77], v240 offset:36864
	global_load_lds_dwordx4 v207, s[36:37]
	v_mfma_f32_32x32x16_bf16 v[34:49], v[168:171], v[176:179], v[34:49]
	ds_read_b128 v[78:81], v236 offset:36864
	v_mfma_f32_32x32x16_bf16 v[50:65], v[190:193], v[194:197], v[50:65]
	s_add_u32 m0, vcc_lo, 0x2000
	ds_read_b128 v[82:85], v237 offset:32768
	global_load_lds_dwordx4 v208, s[36:37]
	v_mfma_f32_32x32x16_bf16 v[18:33], v[202:205], v[194:197], v[18:33]
	ds_read_b128 v[86:89], v241 offset:32768
	v_mfma_f32_32x32x16_bf16 v[2:17], v[202:205], v[198:201], v[2:17]
	s_add_u32 m0, vcc_lo, 0x3000
	ds_read_b128 v[90:93], v241 offset:36864
	global_load_lds_dwordx4 v209, s[36:37]
	v_mfma_f32_32x32x16_bf16 v[34:49], v[190:193], v[198:201], v[34:49]
	ds_read_b128 v[94:97], v237 offset:36864
	s_waitcnt lgkmcnt(6)
	v_mfma_f32_32x32x16_bf16 v[50:65], v[66:69], v[70:73], v[50:65]
	s_add_u32 m0, vcc_lo, 0x4000
	ds_read_b128 v[168:171], v238 offset:32768
	global_load_lds_dwordx4 v210, s[38:39]
	s_waitcnt lgkmcnt(5)
	v_mfma_f32_32x32x16_bf16 v[18:33], v[78:81], v[70:73], v[18:33]
	ds_read_b128 v[172:175], v242 offset:32768
	v_mfma_f32_32x32x16_bf16 v[2:17], v[78:81], v[74:77], v[2:17]
	s_add_u32 m0, vcc_lo, 0x5000
	ds_read_b128 v[176:179], v242 offset:36864
	global_load_lds_dwordx4 v211, s[38:39]
	v_mfma_f32_32x32x16_bf16 v[34:49], v[66:69], v[74:77], v[34:49]
	ds_read_b128 v[180:183], v238 offset:36864
	s_waitcnt lgkmcnt(6)
	v_mfma_f32_32x32x16_bf16 v[50:65], v[82:85], v[86:89], v[50:65]
	s_add_u32 m0, vcc_lo, 0x6000
	ds_read_b128 v[190:193], v239 offset:32768
	global_load_lds_dwordx4 v212, s[38:39]
	s_waitcnt lgkmcnt(5)
	v_mfma_f32_32x32x16_bf16 v[18:33], v[94:97], v[86:89], v[18:33]
	ds_read_b128 v[194:197], v243 offset:32768
	v_mfma_f32_32x32x16_bf16 v[2:17], v[94:97], v[90:93], v[2:17]
	s_add_u32 m0, vcc_lo, 0x7000
	ds_read_b128 v[198:201], v243 offset:36864
	global_load_lds_dwordx4 v213, s[38:39]
	v_mfma_f32_32x32x16_bf16 v[34:49], v[82:85], v[90:93], v[34:49]
	ds_read_b128 v[202:205], v239 offset:36864
	s_add_u32 s36, s36, 0x80
	s_addc_u32 s37, s37, 0
	s_add_u32 s38, s38, 0x80
	s_addc_u32 s39, s39, 0
	s_waitcnt vmcnt(0) lgkmcnt(0)
	s_barrier
	v_mfma_f32_32x32x16_bf16 v[50:65], v[168:171], v[172:175], v[50:65]
	s_add_u32 m0, vcc_lo, 0x8000
	ds_read_b128 v[66:69], v236
	global_load_lds_dwordx4 v206, s[36:37]
	s_setprio 3
	v_mfma_f32_32x32x16_bf16 v[18:33], v[180:183], v[172:175], v[18:33]
	ds_read_b128 v[70:73], v240
	v_mfma_f32_32x32x16_bf16 v[2:17], v[180:183], v[176:179], v[2:17]
	s_add_u32 m0, vcc_lo, 0x9000
	ds_read_b128 v[74:77], v240 offset:4096
	global_load_lds_dwordx4 v207, s[36:37]
	v_mfma_f32_32x32x16_bf16 v[34:49], v[168:171], v[176:179], v[34:49]
	ds_read_b128 v[78:81], v236 offset:4096
	v_mfma_f32_32x32x16_bf16 v[50:65], v[190:193], v[194:197], v[50:65]
	s_add_u32 m0, vcc_lo, 0xa000
	ds_read_b128 v[82:85], v237
	global_load_lds_dwordx4 v208, s[36:37]
	v_mfma_f32_32x32x16_bf16 v[18:33], v[202:205], v[194:197], v[18:33]
	ds_read_b128 v[86:89], v241
	v_mfma_f32_32x32x16_bf16 v[2:17], v[202:205], v[198:201], v[2:17]
	s_add_u32 m0, vcc_lo, 0xb000
	ds_read_b128 v[90:93], v241 offset:4096
	global_load_lds_dwordx4 v209, s[36:37]
	v_mfma_f32_32x32x16_bf16 v[34:49], v[190:193], v[198:201], v[34:49]
	ds_read_b128 v[94:97], v237 offset:4096
	s_waitcnt lgkmcnt(6)
	v_mfma_f32_32x32x16_bf16 v[50:65], v[66:69], v[70:73], v[50:65]
	s_add_u32 m0, vcc_lo, 0xc000
	ds_read_b128 v[168:171], v238
	global_load_lds_dwordx4 v210, s[38:39]
	s_waitcnt lgkmcnt(5)
	v_mfma_f32_32x32x16_bf16 v[18:33], v[78:81], v[70:73], v[18:33]
	ds_read_b128 v[172:175], v242
	v_mfma_f32_32x32x16_bf16 v[2:17], v[78:81], v[74:77], v[2:17]
	s_add_u32 m0, vcc_lo, 0xd000
	ds_read_b128 v[176:179], v242 offset:4096
	global_load_lds_dwordx4 v211, s[38:39]
	v_mfma_f32_32x32x16_bf16 v[34:49], v[66:69], v[74:77], v[34:49]
	ds_read_b128 v[180:183], v238 offset:4096
	s_waitcnt lgkmcnt(6)
	v_mfma_f32_32x32x16_bf16 v[50:65], v[82:85], v[86:89], v[50:65]
	s_add_u32 m0, vcc_lo, 0xe000
	ds_read_b128 v[190:193], v239
	global_load_lds_dwordx4 v212, s[38:39]
	s_waitcnt lgkmcnt(5)
	v_mfma_f32_32x32x16_bf16 v[18:33], v[94:97], v[86:89], v[18:33]
	ds_read_b128 v[194:197], v243
	v_mfma_f32_32x32x16_bf16 v[2:17], v[94:97], v[90:93], v[2:17]
	s_add_u32 m0, vcc_lo, 0xf000
	ds_read_b128 v[198:201], v243 offset:4096
	global_load_lds_dwordx4 v213, s[38:39]
	v_mfma_f32_32x32x16_bf16 v[34:49], v[82:85], v[90:93], v[34:49]
	ds_read_b128 v[202:205], v239 offset:4096
	s_add_u32 s36, s36, 0x80
	s_addc_u32 s37, s37, 0
	s_add_u32 s38, s38, 0x80
	s_addc_u32 s39, s39, 0
	s_waitcnt vmcnt(0) lgkmcnt(0)
	s_barrier
	v_mfma_f32_32x32x16_bf16 v[50:65], v[168:171], v[172:175], v[50:65]
	s_mov_b32 m0, vcc_lo
	ds_read_b128 v[66:69], v236 offset:32768
	global_load_lds_dwordx4 v206, s[36:37]
	s_setprio 3
	v_mfma_f32_32x32x16_bf16 v[18:33], v[180:183], v[172:175], v[18:33]
	ds_read_b128 v[70:73], v240 offset:32768
	v_mfma_f32_32x32x16_bf16 v[2:17], v[180:183], v[176:179], v[2:17]
	s_add_u32 m0, vcc_lo, 0x1000
	ds_read_b128 v[74:77], v240 offset:36864
	global_load_lds_dwordx4 v207, s[36:37]
	v_mfma_f32_32x32x16_bf16 v[34:49], v[168:171], v[176:179], v[34:49]
	ds_read_b128 v[78:81], v236 offset:36864
	v_mfma_f32_32x32x16_bf16 v[50:65], v[190:193], v[194:197], v[50:65]
	s_add_u32 m0, vcc_lo, 0x2000
	ds_read_b128 v[82:85], v237 offset:32768
	global_load_lds_dwordx4 v208, s[36:37]
	v_mfma_f32_32x32x16_bf16 v[18:33], v[202:205], v[194:197], v[18:33]
	ds_read_b128 v[86:89], v241 offset:32768
	v_mfma_f32_32x32x16_bf16 v[2:17], v[202:205], v[198:201], v[2:17]
	s_add_u32 m0, vcc_lo, 0x3000
	ds_read_b128 v[90:93], v241 offset:36864
	global_load_lds_dwordx4 v209, s[36:37]
	v_mfma_f32_32x32x16_bf16 v[34:49], v[190:193], v[198:201], v[34:49]
	ds_read_b128 v[94:97], v237 offset:36864
	s_waitcnt lgkmcnt(6)
	v_mfma_f32_32x32x16_bf16 v[50:65], v[66:69], v[70:73], v[50:65]
	s_add_u32 m0, vcc_lo, 0x4000
	ds_read_b128 v[168:171], v238 offset:32768
	global_load_lds_dwordx4 v210, s[38:39]
	s_waitcnt lgkmcnt(5)
	v_mfma_f32_32x32x16_bf16 v[18:33], v[78:81], v[70:73], v[18:33]
	ds_read_b128 v[172:175], v242 offset:32768
	v_mfma_f32_32x32x16_bf16 v[2:17], v[78:81], v[74:77], v[2:17]
	s_add_u32 m0, vcc_lo, 0x5000
	ds_read_b128 v[176:179], v242 offset:36864
	global_load_lds_dwordx4 v211, s[38:39]
	v_mfma_f32_32x32x16_bf16 v[34:49], v[66:69], v[74:77], v[34:49]
	ds_read_b128 v[180:183], v238 offset:36864
	s_waitcnt lgkmcnt(6)
	v_mfma_f32_32x32x16_bf16 v[50:65], v[82:85], v[86:89], v[50:65]
	s_add_u32 m0, vcc_lo, 0x6000
	ds_read_b128 v[190:193], v239 offset:32768
	global_load_lds_dwordx4 v212, s[38:39]
	s_waitcnt lgkmcnt(5)
	v_mfma_f32_32x32x16_bf16 v[18:33], v[94:97], v[86:89], v[18:33]
	ds_read_b128 v[194:197], v243 offset:32768
	v_mfma_f32_32x32x16_bf16 v[2:17], v[94:97], v[90:93], v[2:17]
	s_add_u32 m0, vcc_lo, 0x7000
	ds_read_b128 v[198:201], v243 offset:36864
	global_load_lds_dwordx4 v213, s[38:39]
	v_mfma_f32_32x32x16_bf16 v[34:49], v[82:85], v[90:93], v[34:49]
	ds_read_b128 v[202:205], v239 offset:36864
	s_add_u32 s36, s36, 0x80
	s_addc_u32 s37, s37, 0
	s_add_u32 s38, s38, 0x80
	s_addc_u32 s39, s39, 0
	s_waitcnt vmcnt(0) lgkmcnt(0)
	s_barrier
	v_mfma_f32_32x32x16_bf16 v[50:65], v[168:171], v[172:175], v[50:65]
	s_add_u32 m0, vcc_lo, 0x8000
	ds_read_b128 v[66:69], v236
	global_load_lds_dwordx4 v206, s[36:37]
	s_setprio 3
	v_mfma_f32_32x32x16_bf16 v[18:33], v[180:183], v[172:175], v[18:33]
	ds_read_b128 v[70:73], v240
	v_mfma_f32_32x32x16_bf16 v[2:17], v[180:183], v[176:179], v[2:17]
	s_add_u32 m0, vcc_lo, 0x9000
	ds_read_b128 v[74:77], v240 offset:4096
	global_load_lds_dwordx4 v207, s[36:37]
	v_mfma_f32_32x32x16_bf16 v[34:49], v[168:171], v[176:179], v[34:49]
	ds_read_b128 v[78:81], v236 offset:4096
	v_mfma_f32_32x32x16_bf16 v[50:65], v[190:193], v[194:197], v[50:65]
	s_add_u32 m0, vcc_lo, 0xa000
	ds_read_b128 v[82:85], v237
	global_load_lds_dwordx4 v208, s[36:37]
	v_mfma_f32_32x32x16_bf16 v[18:33], v[202:205], v[194:197], v[18:33]
	ds_read_b128 v[86:89], v241
	v_mfma_f32_32x32x16_bf16 v[2:17], v[202:205], v[198:201], v[2:17]
	s_add_u32 m0, vcc_lo, 0xb000
	ds_read_b128 v[90:93], v241 offset:4096
	global_load_lds_dwordx4 v209, s[36:37]
	v_mfma_f32_32x32x16_bf16 v[34:49], v[190:193], v[198:201], v[34:49]
	ds_read_b128 v[94:97], v237 offset:4096
	s_waitcnt lgkmcnt(6)
	v_mfma_f32_32x32x16_bf16 v[50:65], v[66:69], v[70:73], v[50:65]
	s_add_u32 m0, vcc_lo, 0xc000
	ds_read_b128 v[168:171], v238
	global_load_lds_dwordx4 v210, s[38:39]
	s_waitcnt lgkmcnt(5)
	v_mfma_f32_32x32x16_bf16 v[18:33], v[78:81], v[70:73], v[18:33]
	ds_read_b128 v[172:175], v242
	v_mfma_f32_32x32x16_bf16 v[2:17], v[78:81], v[74:77], v[2:17]
	s_add_u32 m0, vcc_lo, 0xd000
	ds_read_b128 v[176:179], v242 offset:4096
	global_load_lds_dwordx4 v211, s[38:39]
	v_mfma_f32_32x32x16_bf16 v[34:49], v[66:69], v[74:77], v[34:49]
	ds_read_b128 v[180:183], v238 offset:4096
	s_waitcnt lgkmcnt(6)
	v_mfma_f32_32x32x16_bf16 v[50:65], v[82:85], v[86:89], v[50:65]
	s_add_u32 m0, vcc_lo, 0xe000
	ds_read_b128 v[190:193], v239
	global_load_lds_dwordx4 v212, s[38:39]
	s_waitcnt lgkmcnt(5)
	v_mfma_f32_32x32x16_bf16 v[18:33], v[94:97], v[86:89], v[18:33]
	ds_read_b128 v[194:197], v243
	v_mfma_f32_32x32x16_bf16 v[2:17], v[94:97], v[90:93], v[2:17]
	s_add_u32 m0, vcc_lo, 0xf000
	ds_read_b128 v[198:201], v243 offset:4096
	global_load_lds_dwordx4 v213, s[38:39]
	v_mfma_f32_32x32x16_bf16 v[34:49], v[82:85], v[90:93], v[34:49]
	ds_read_b128 v[202:205], v239 offset:4096
	s_add_u32 s36, s36, 0x80
	s_addc_u32 s37, s37, 0
	s_add_u32 s38, s38, 0x80
	s_addc_u32 s39, s39, 0
	s_waitcnt vmcnt(0) lgkmcnt(0)
	s_barrier
	v_mfma_f32_32x32x16_bf16 v[50:65], v[168:171], v[172:175], v[50:65]
	s_mov_b32 m0, vcc_lo
	ds_read_b128 v[66:69], v236 offset:32768
	global_load_lds_dwordx4 v206, s[36:37]
	s_setprio 3
	v_mfma_f32_32x32x16_bf16 v[18:33], v[180:183], v[172:175], v[18:33]
	ds_read_b128 v[70:73], v240 offset:32768
	v_mfma_f32_32x32x16_bf16 v[2:17], v[180:183], v[176:179], v[2:17]
	s_add_u32 m0, vcc_lo, 0x1000
	ds_read_b128 v[74:77], v240 offset:36864
	global_load_lds_dwordx4 v207, s[36:37]
	v_mfma_f32_32x32x16_bf16 v[34:49], v[168:171], v[176:179], v[34:49]
	ds_read_b128 v[78:81], v236 offset:36864
	v_mfma_f32_32x32x16_bf16 v[50:65], v[190:193], v[194:197], v[50:65]
	s_add_u32 m0, vcc_lo, 0x2000
	ds_read_b128 v[82:85], v237 offset:32768
	global_load_lds_dwordx4 v208, s[36:37]
	v_mfma_f32_32x32x16_bf16 v[18:33], v[202:205], v[194:197], v[18:33]
	ds_read_b128 v[86:89], v241 offset:32768
	v_mfma_f32_32x32x16_bf16 v[2:17], v[202:205], v[198:201], v[2:17]
	s_add_u32 m0, vcc_lo, 0x3000
	ds_read_b128 v[90:93], v241 offset:36864
	global_load_lds_dwordx4 v209, s[36:37]
	v_mfma_f32_32x32x16_bf16 v[34:49], v[190:193], v[198:201], v[34:49]
	ds_read_b128 v[94:97], v237 offset:36864
	s_waitcnt lgkmcnt(6)
	v_mfma_f32_32x32x16_bf16 v[50:65], v[66:69], v[70:73], v[50:65]
	s_add_u32 m0, vcc_lo, 0x4000
	ds_read_b128 v[168:171], v238 offset:32768
	global_load_lds_dwordx4 v210, s[38:39]
	s_waitcnt lgkmcnt(5)
	v_mfma_f32_32x32x16_bf16 v[18:33], v[78:81], v[70:73], v[18:33]
	ds_read_b128 v[172:175], v242 offset:32768
	v_mfma_f32_32x32x16_bf16 v[2:17], v[78:81], v[74:77], v[2:17]
	s_add_u32 m0, vcc_lo, 0x5000
	ds_read_b128 v[176:179], v242 offset:36864
	global_load_lds_dwordx4 v211, s[38:39]
	v_mfma_f32_32x32x16_bf16 v[34:49], v[66:69], v[74:77], v[34:49]
	ds_read_b128 v[180:183], v238 offset:36864
	s_waitcnt lgkmcnt(6)
	v_mfma_f32_32x32x16_bf16 v[50:65], v[82:85], v[86:89], v[50:65]
	s_add_u32 m0, vcc_lo, 0x6000
	ds_read_b128 v[190:193], v239 offset:32768
	global_load_lds_dwordx4 v212, s[38:39]
	s_waitcnt lgkmcnt(5)
	v_mfma_f32_32x32x16_bf16 v[18:33], v[94:97], v[86:89], v[18:33]
	ds_read_b128 v[194:197], v243 offset:32768
	v_mfma_f32_32x32x16_bf16 v[2:17], v[94:97], v[90:93], v[2:17]
	s_add_u32 m0, vcc_lo, 0x7000
	ds_read_b128 v[198:201], v243 offset:36864
	global_load_lds_dwordx4 v213, s[38:39]
	v_mfma_f32_32x32x16_bf16 v[34:49], v[82:85], v[90:93], v[34:49]
	ds_read_b128 v[202:205], v239 offset:36864
	s_add_u32 s36, s36, 0x80
	s_addc_u32 s37, s37, 0
	s_add_u32 s38, s38, 0x80
	s_addc_u32 s39, s39, 0
	s_waitcnt vmcnt(0) lgkmcnt(0)
	s_barrier
	v_mfma_f32_32x32x16_bf16 v[50:65], v[168:171], v[172:175], v[50:65]
	s_add_u32 m0, vcc_lo, 0x8000
	ds_read_b128 v[66:69], v236
	global_load_lds_dwordx4 v206, s[36:37]
	s_setprio 3
	v_mfma_f32_32x32x16_bf16 v[18:33], v[180:183], v[172:175], v[18:33]
	ds_read_b128 v[70:73], v240
	v_mfma_f32_32x32x16_bf16 v[2:17], v[180:183], v[176:179], v[2:17]
	s_add_u32 m0, vcc_lo, 0x9000
	ds_read_b128 v[74:77], v240 offset:4096
	global_load_lds_dwordx4 v207, s[36:37]
	v_mfma_f32_32x32x16_bf16 v[34:49], v[168:171], v[176:179], v[34:49]
	ds_read_b128 v[78:81], v236 offset:4096
	v_mfma_f32_32x32x16_bf16 v[50:65], v[190:193], v[194:197], v[50:65]
	s_add_u32 m0, vcc_lo, 0xa000
	ds_read_b128 v[82:85], v237
	global_load_lds_dwordx4 v208, s[36:37]
	v_mfma_f32_32x32x16_bf16 v[18:33], v[202:205], v[194:197], v[18:33]
	ds_read_b128 v[86:89], v241
	v_mfma_f32_32x32x16_bf16 v[2:17], v[202:205], v[198:201], v[2:17]
	s_add_u32 m0, vcc_lo, 0xb000
	ds_read_b128 v[90:93], v241 offset:4096
	global_load_lds_dwordx4 v209, s[36:37]
	v_mfma_f32_32x32x16_bf16 v[34:49], v[190:193], v[198:201], v[34:49]
	ds_read_b128 v[94:97], v237 offset:4096
	s_waitcnt lgkmcnt(6)
	v_mfma_f32_32x32x16_bf16 v[50:65], v[66:69], v[70:73], v[50:65]
	s_add_u32 m0, vcc_lo, 0xc000
	ds_read_b128 v[168:171], v238
	global_load_lds_dwordx4 v210, s[38:39]
	s_waitcnt lgkmcnt(5)
	v_mfma_f32_32x32x16_bf16 v[18:33], v[78:81], v[70:73], v[18:33]
	ds_read_b128 v[172:175], v242
	v_mfma_f32_32x32x16_bf16 v[2:17], v[78:81], v[74:77], v[2:17]
	s_add_u32 m0, vcc_lo, 0xd000
	ds_read_b128 v[176:179], v242 offset:4096
	global_load_lds_dwordx4 v211, s[38:39]
	v_mfma_f32_32x32x16_bf16 v[34:49], v[66:69], v[74:77], v[34:49]
	ds_read_b128 v[180:183], v238 offset:4096
	s_waitcnt lgkmcnt(6)
	v_mfma_f32_32x32x16_bf16 v[50:65], v[82:85], v[86:89], v[50:65]
	s_add_u32 m0, vcc_lo, 0xe000
	ds_read_b128 v[190:193], v239
	global_load_lds_dwordx4 v212, s[38:39]
	s_waitcnt lgkmcnt(5)
	v_mfma_f32_32x32x16_bf16 v[18:33], v[94:97], v[86:89], v[18:33]
	ds_read_b128 v[194:197], v243
	v_mfma_f32_32x32x16_bf16 v[2:17], v[94:97], v[90:93], v[2:17]
	s_add_u32 m0, vcc_lo, 0xf000
	ds_read_b128 v[198:201], v243 offset:4096
	global_load_lds_dwordx4 v213, s[38:39]
	v_mfma_f32_32x32x16_bf16 v[34:49], v[82:85], v[90:93], v[34:49]
	ds_read_b128 v[202:205], v239 offset:4096
	s_add_u32 s38, s38, 0x80
	s_addc_u32 s39, s39, 0
	s_waitcnt vmcnt(0) lgkmcnt(0)
	s_barrier
	v_mfma_f32_32x32x16_bf16 v[50:65], v[168:171], v[172:175], v[50:65]
	s_mov_b32 m0, vcc_lo
	ds_read_b128 v[66:69], v236 offset:32768
	global_load_lds_dwordx4 v222, s[40:41]
	s_setprio 3
	v_mfma_f32_32x32x16_bf16 v[18:33], v[180:183], v[172:175], v[18:33]
	ds_read_b128 v[70:73], v240 offset:32768
	v_mfma_f32_32x32x16_bf16 v[2:17], v[180:183], v[176:179], v[2:17]
	s_add_u32 m0, vcc_lo, 0x1000
	ds_read_b128 v[74:77], v240 offset:36864
	global_load_lds_dwordx4 v223, s[40:41]
	v_mfma_f32_32x32x16_bf16 v[34:49], v[168:171], v[176:179], v[34:49]
	ds_read_b128 v[78:81], v236 offset:36864
	v_mfma_f32_32x32x16_bf16 v[50:65], v[190:193], v[194:197], v[50:65]
	s_add_u32 m0, vcc_lo, 0x2000
	ds_read_b128 v[82:85], v237 offset:32768
	global_load_lds_dwordx4 v224, s[40:41]
	v_mfma_f32_32x32x16_bf16 v[18:33], v[202:205], v[194:197], v[18:33]
	ds_read_b128 v[86:89], v241 offset:32768
	v_mfma_f32_32x32x16_bf16 v[2:17], v[202:205], v[198:201], v[2:17]
	s_add_u32 m0, vcc_lo, 0x3000
	ds_read_b128 v[90:93], v241 offset:36864
	global_load_lds_dwordx4 v225, s[40:41]
	v_mfma_f32_32x32x16_bf16 v[34:49], v[190:193], v[198:201], v[34:49]
	ds_read_b128 v[94:97], v237 offset:36864
	s_waitcnt lgkmcnt(6)
	v_mfma_f32_32x32x16_bf16 v[50:65], v[66:69], v[70:73], v[50:65]
	s_add_u32 m0, vcc_lo, 0x4000
	ds_read_b128 v[168:171], v238 offset:32768
	global_load_lds_dwordx4 v222, s[42:43]
	s_waitcnt lgkmcnt(5)
	v_mfma_f32_32x32x16_bf16 v[18:33], v[78:81], v[70:73], v[18:33]
	ds_read_b128 v[172:175], v242 offset:32768
	v_mfma_f32_32x32x16_bf16 v[2:17], v[78:81], v[74:77], v[2:17]
	s_add_u32 m0, vcc_lo, 0x5000
	ds_read_b128 v[176:179], v242 offset:36864
	global_load_lds_dwordx4 v223, s[42:43]
	v_mfma_f32_32x32x16_bf16 v[34:49], v[66:69], v[74:77], v[34:49]
	ds_read_b128 v[180:183], v238 offset:36864
	s_waitcnt lgkmcnt(6)
	v_mfma_f32_32x32x16_bf16 v[50:65], v[82:85], v[86:89], v[50:65]
	s_add_u32 m0, vcc_lo, 0x6000
	ds_read_b128 v[190:193], v239 offset:32768
	global_load_lds_dwordx4 v224, s[42:43]
	s_waitcnt lgkmcnt(5)
	v_mfma_f32_32x32x16_bf16 v[18:33], v[94:97], v[86:89], v[18:33]
	ds_read_b128 v[194:197], v243 offset:32768
	v_mfma_f32_32x32x16_bf16 v[2:17], v[94:97], v[90:93], v[2:17]
	s_add_u32 m0, vcc_lo, 0x7000
	ds_read_b128 v[198:201], v243 offset:36864
	global_load_lds_dwordx4 v225, s[42:43]
	v_mfma_f32_32x32x16_bf16 v[34:49], v[82:85], v[90:93], v[34:49]
	ds_read_b128 v[202:205], v239 offset:36864
	s_add_u32 s40, s40, 0x800
	s_addc_u32 s41, s41, 0
	s_add_u32 s42, s42, 0x800
	s_addc_u32 s43, s43, 0
	s_waitcnt vmcnt(0) lgkmcnt(0)
	s_barrier
	v_mfma_f32_32x32x16_bf16 v[50:65], v[168:171], v[172:175], v[50:65]
	v_mfma_f32_32x32x16_bf16 v[18:33], v[180:183], v[172:175], v[18:33]
	v_mfma_f32_32x32x16_bf16 v[2:17], v[180:183], v[176:179], v[2:17]
	v_mfma_f32_32x32x16_bf16 v[34:49], v[168:171], v[176:179], v[34:49]
	v_mfma_f32_32x32x16_bf16 v[50:65], v[190:193], v[194:197], v[50:65]
	v_mfma_f32_32x32x16_bf16 v[18:33], v[202:205], v[194:197], v[18:33]
	v_mfma_f32_32x32x16_bf16 v[2:17], v[202:205], v[198:201], v[2:17]
	v_mfma_f32_32x32x16_bf16 v[34:49], v[190:193], v[198:201], v[34:49]
	s_setprio 0
	ds_read_u16 v66, v244 offset:0
	ds_read_u16 v67, v244 offset:128
	ds_read_u16 v68, v245 offset:256
	ds_read_u16 v69, v245 offset:384
	ds_read_u16 v70, v244 offset:1088
	ds_read_u16 v71, v244 offset:1216
	ds_read_u16 v72, v245 offset:1344
	ds_read_u16 v73, v245 offset:1472
	s_nop 7
	s_nop 7
	ds_read_u16 v74, v244 offset:2048
	ds_read_u16 v75, v244 offset:2176
	ds_read_u16 v76, v245 offset:2304
	ds_read_u16 v77, v245 offset:2432
	ds_read_u16 v78, v244 offset:3136
	ds_read_u16 v79, v244 offset:3264
	ds_read_u16 v80, v245 offset:3392
	ds_read_u16 v81, v245 offset:3520
	s_waitcnt lgkmcnt(8)
	v_lshlrev_b32_e32 v66, 16, v66
	v_lshlrev_b32_e32 v67, 16, v67
	v_lshlrev_b32_e32 v68, 16, v68
	v_lshlrev_b32_e32 v69, 16, v69
	v_mul_f32_e32 v66, 0xbfb8aa3b, v66
	v_mul_f32_e32 v67, 0xbfb8aa3b, v67
	v_mul_f32_e32 v68, 0xbfb8aa3b, v68
	v_mul_f32_e32 v69, 0xbfb8aa3b, v69
	v_exp_f32_e32 v66, v66
	v_exp_f32_e32 v67, v67
	v_exp_f32_e32 v68, v68
	v_exp_f32_e32 v69, v69
	v_add_f32_e32 v66, 1.0, v66
	v_add_f32_e32 v67, 1.0, v67
	v_add_f32_e32 v68, 1.0, v68
	v_add_f32_e32 v69, 1.0, v69
	v_rcp_f32_e32 v66, v66
	v_rcp_f32_e32 v67, v67
	v_rcp_f32_e32 v68, v68
	v_rcp_f32_e32 v69, v69
	s_nop 0
	v_pk_fma_f32 v[166:167], v[50:51], v[66:67], v[166:167]
	v_pk_fma_f32 v[164:165], v[52:53], v[68:69], v[164:165]
	v_lshlrev_b32_e32 v70, 16, v70
	v_lshlrev_b32_e32 v71, 16, v71
	v_lshlrev_b32_e32 v72, 16, v72
	v_lshlrev_b32_e32 v73, 16, v73
	v_mul_f32_e32 v70, 0xbfb8aa3b, v70
	v_mul_f32_e32 v71, 0xbfb8aa3b, v71
	v_mul_f32_e32 v72, 0xbfb8aa3b, v72
	v_mul_f32_e32 v73, 0xbfb8aa3b, v73
	v_exp_f32_e32 v70, v70
	v_exp_f32_e32 v71, v71
	v_exp_f32_e32 v72, v72
	v_exp_f32_e32 v73, v73
	v_add_f32_e32 v70, 1.0, v70
	v_add_f32_e32 v71, 1.0, v71
	v_add_f32_e32 v72, 1.0, v72
	v_add_f32_e32 v73, 1.0, v73
	v_rcp_f32_e32 v70, v70
	v_rcp_f32_e32 v71, v71
	v_rcp_f32_e32 v72, v72
	v_rcp_f32_e32 v73, v73
	s_nop 0
	v_pk_fma_f32 v[162:163], v[54:55], v[70:71], v[162:163]
	v_pk_fma_f32 v[160:161], v[56:57], v[72:73], v[160:161]
	ds_read_u16 v82, v244 offset:4096
	ds_read_u16 v83, v244 offset:4224
	ds_read_u16 v84, v245 offset:4352
	ds_read_u16 v85, v245 offset:4480
	ds_read_u16 v86, v244 offset:5184
	ds_read_u16 v87, v244 offset:5312
	ds_read_u16 v88, v245 offset:5440
	ds_read_u16 v89, v245 offset:5568
	s_waitcnt lgkmcnt(8)
	v_lshlrev_b32_e32 v74, 16, v74
	v_lshlrev_b32_e32 v75, 16, v75
	v_lshlrev_b32_e32 v76, 16, v76
	v_lshlrev_b32_e32 v77, 16, v77
	v_mul_f32_e32 v74, 0xbfb8aa3b, v74
	v_mul_f32_e32 v75, 0xbfb8aa3b, v75
	v_mul_f32_e32 v76, 0xbfb8aa3b, v76
	v_mul_f32_e32 v77, 0xbfb8aa3b, v77
	v_exp_f32_e32 v74, v74
	v_exp_f32_e32 v75, v75
	v_exp_f32_e32 v76, v76
	v_exp_f32_e32 v77, v77
	v_add_f32_e32 v74, 1.0, v74
	v_add_f32_e32 v75, 1.0, v75
	v_add_f32_e32 v76, 1.0, v76
	v_add_f32_e32 v77, 1.0, v77
	v_rcp_f32_e32 v74, v74
	v_rcp_f32_e32 v75, v75
	v_rcp_f32_e32 v76, v76
	v_rcp_f32_e32 v77, v77
	s_nop 0
	v_pk_fma_f32 v[158:159], v[58:59], v[74:75], v[158:159]
	v_pk_fma_f32 v[156:157], v[60:61], v[76:77], v[156:157]
	v_lshlrev_b32_e32 v78, 16, v78
	v_lshlrev_b32_e32 v79, 16, v79
	v_lshlrev_b32_e32 v80, 16, v80
	v_lshlrev_b32_e32 v81, 16, v81
	v_mul_f32_e32 v78, 0xbfb8aa3b, v78
	v_mul_f32_e32 v79, 0xbfb8aa3b, v79
	v_mul_f32_e32 v80, 0xbfb8aa3b, v80
	v_mul_f32_e32 v81, 0xbfb8aa3b, v81
	v_exp_f32_e32 v78, v78
	v_exp_f32_e32 v79, v79
	v_exp_f32_e32 v80, v80
	v_exp_f32_e32 v81, v81
	v_add_f32_e32 v78, 1.0, v78
	v_add_f32_e32 v79, 1.0, v79
	v_add_f32_e32 v80, 1.0, v80
	v_add_f32_e32 v81, 1.0, v81
	v_rcp_f32_e32 v78, v78
	v_rcp_f32_e32 v79, v79
	v_rcp_f32_e32 v80, v80
	v_rcp_f32_e32 v81, v81
	s_nop 0
	v_pk_fma_f32 v[154:155], v[62:63], v[78:79], v[154:155]
	v_pk_fma_f32 v[152:153], v[64:65], v[80:81], v[152:153]
	ds_read_u16 v90, v244 offset:6144
	ds_read_u16 v91, v244 offset:6272
	ds_read_u16 v92, v245 offset:6400
	ds_read_u16 v93, v245 offset:6528
	ds_read_u16 v94, v244 offset:7232
	ds_read_u16 v95, v244 offset:7360
	ds_read_u16 v96, v245 offset:7488
	ds_read_u16 v97, v245 offset:7616
	s_waitcnt lgkmcnt(8)
	v_lshlrev_b32_e32 v82, 16, v82
	v_lshlrev_b32_e32 v83, 16, v83
	v_lshlrev_b32_e32 v84, 16, v84
	v_lshlrev_b32_e32 v85, 16, v85
	v_mul_f32_e32 v82, 0xbfb8aa3b, v82
	v_mul_f32_e32 v83, 0xbfb8aa3b, v83
	v_mul_f32_e32 v84, 0xbfb8aa3b, v84
	v_mul_f32_e32 v85, 0xbfb8aa3b, v85
	v_exp_f32_e32 v82, v82
	v_exp_f32_e32 v83, v83
	v_exp_f32_e32 v84, v84
	v_exp_f32_e32 v85, v85
	v_add_f32_e32 v82, 1.0, v82
	v_add_f32_e32 v83, 1.0, v83
	v_add_f32_e32 v84, 1.0, v84
	v_add_f32_e32 v85, 1.0, v85
	v_rcp_f32_e32 v82, v82
	v_rcp_f32_e32 v83, v83
	v_rcp_f32_e32 v84, v84
	v_rcp_f32_e32 v85, v85
	s_nop 0
	v_pk_fma_f32 v[130:131], v[18:19], v[82:83], v[130:131]
	v_pk_fma_f32 v[128:129], v[20:21], v[84:85], v[128:129]
	v_lshlrev_b32_e32 v86, 16, v86
	v_lshlrev_b32_e32 v87, 16, v87
	v_lshlrev_b32_e32 v88, 16, v88
	v_lshlrev_b32_e32 v89, 16, v89
	v_mul_f32_e32 v86, 0xbfb8aa3b, v86
	v_mul_f32_e32 v87, 0xbfb8aa3b, v87
	v_mul_f32_e32 v88, 0xbfb8aa3b, v88
	v_mul_f32_e32 v89, 0xbfb8aa3b, v89
	v_exp_f32_e32 v86, v86
	v_exp_f32_e32 v87, v87
	v_exp_f32_e32 v88, v88
	v_exp_f32_e32 v89, v89
	v_add_f32_e32 v86, 1.0, v86
	v_add_f32_e32 v87, 1.0, v87
	v_add_f32_e32 v88, 1.0, v88
	v_add_f32_e32 v89, 1.0, v89
	v_rcp_f32_e32 v86, v86
	v_rcp_f32_e32 v87, v87
	v_rcp_f32_e32 v88, v88
	v_rcp_f32_e32 v89, v89
	s_nop 0
	v_pk_fma_f32 v[126:127], v[22:23], v[86:87], v[126:127]
	v_pk_fma_f32 v[124:125], v[24:25], v[88:89], v[124:125]
	ds_read_u16 v168, v244 offset:4160
	ds_read_u16 v169, v244 offset:4288
	ds_read_u16 v170, v245 offset:4416
	ds_read_u16 v171, v245 offset:4544
	ds_read_u16 v172, v244 offset:5120
	ds_read_u16 v173, v244 offset:5248
	ds_read_u16 v174, v245 offset:5376
	ds_read_u16 v175, v245 offset:5504
	s_waitcnt lgkmcnt(8)
	v_lshlrev_b32_e32 v90, 16, v90
	v_lshlrev_b32_e32 v91, 16, v91
	v_lshlrev_b32_e32 v92, 16, v92
	v_lshlrev_b32_e32 v93, 16, v93
	v_mul_f32_e32 v90, 0xbfb8aa3b, v90
	v_mul_f32_e32 v91, 0xbfb8aa3b, v91
	v_mul_f32_e32 v92, 0xbfb8aa3b, v92
	v_mul_f32_e32 v93, 0xbfb8aa3b, v93
	v_exp_f32_e32 v90, v90
	v_exp_f32_e32 v91, v91
	v_exp_f32_e32 v92, v92
	v_exp_f32_e32 v93, v93
	v_add_f32_e32 v90, 1.0, v90
	v_add_f32_e32 v91, 1.0, v91
	v_add_f32_e32 v92, 1.0, v92
	v_add_f32_e32 v93, 1.0, v93
	v_rcp_f32_e32 v90, v90
	v_rcp_f32_e32 v91, v91
	v_rcp_f32_e32 v92, v92
	v_rcp_f32_e32 v93, v93
	s_nop 0
	v_pk_fma_f32 v[122:123], v[26:27], v[90:91], v[122:123]
	v_pk_fma_f32 v[120:121], v[28:29], v[92:93], v[120:121]
	v_lshlrev_b32_e32 v94, 16, v94
	v_lshlrev_b32_e32 v95, 16, v95
	v_lshlrev_b32_e32 v96, 16, v96
	v_lshlrev_b32_e32 v97, 16, v97
	v_mul_f32_e32 v94, 0xbfb8aa3b, v94
	v_mul_f32_e32 v95, 0xbfb8aa3b, v95
	v_mul_f32_e32 v96, 0xbfb8aa3b, v96
	v_mul_f32_e32 v97, 0xbfb8aa3b, v97
	v_exp_f32_e32 v94, v94
	v_exp_f32_e32 v95, v95
	v_exp_f32_e32 v96, v96
	v_exp_f32_e32 v97, v97
	v_add_f32_e32 v94, 1.0, v94
	v_add_f32_e32 v95, 1.0, v95
	v_add_f32_e32 v96, 1.0, v96
	v_add_f32_e32 v97, 1.0, v97
	v_rcp_f32_e32 v94, v94
	v_rcp_f32_e32 v95, v95
	v_rcp_f32_e32 v96, v96
	v_rcp_f32_e32 v97, v97
	s_nop 0
	v_pk_fma_f32 v[118:119], v[30:31], v[94:95], v[118:119]
	v_pk_fma_f32 v[116:117], v[32:33], v[96:97], v[116:117]
	ds_read_u16 v176, v244 offset:6208
	ds_read_u16 v177, v244 offset:6336
	ds_read_u16 v178, v245 offset:6464
	ds_read_u16 v179, v245 offset:6592
	ds_read_u16 v180, v244 offset:7168
	ds_read_u16 v181, v244 offset:7296
	ds_read_u16 v182, v245 offset:7424
	ds_read_u16 v183, v245 offset:7552
	s_waitcnt lgkmcnt(8)
	v_lshlrev_b32_e32 v168, 16, v168
	v_lshlrev_b32_e32 v169, 16, v169
	v_lshlrev_b32_e32 v170, 16, v170
	v_lshlrev_b32_e32 v171, 16, v171
	v_mul_f32_e32 v168, 0xbfb8aa3b, v168
	v_mul_f32_e32 v169, 0xbfb8aa3b, v169
	v_mul_f32_e32 v170, 0xbfb8aa3b, v170
	v_mul_f32_e32 v171, 0xbfb8aa3b, v171
	v_exp_f32_e32 v168, v168
	v_exp_f32_e32 v169, v169
	v_exp_f32_e32 v170, v170
	v_exp_f32_e32 v171, v171
	v_add_f32_e32 v168, 1.0, v168
	v_add_f32_e32 v169, 1.0, v169
	v_add_f32_e32 v170, 1.0, v170
	v_add_f32_e32 v171, 1.0, v171
	v_rcp_f32_e32 v168, v168
	v_rcp_f32_e32 v169, v169
	v_rcp_f32_e32 v170, v170
	v_rcp_f32_e32 v171, v171
	s_nop 0
	v_pk_fma_f32 v[114:115], v[2:3], v[168:169], v[114:115]
	v_pk_fma_f32 v[112:113], v[4:5], v[170:171], v[112:113]
	v_lshlrev_b32_e32 v172, 16, v172
	v_lshlrev_b32_e32 v173, 16, v173
	v_lshlrev_b32_e32 v174, 16, v174
	v_lshlrev_b32_e32 v175, 16, v175
	v_mul_f32_e32 v172, 0xbfb8aa3b, v172
	v_mul_f32_e32 v173, 0xbfb8aa3b, v173
	v_mul_f32_e32 v174, 0xbfb8aa3b, v174
	v_mul_f32_e32 v175, 0xbfb8aa3b, v175
	v_exp_f32_e32 v172, v172
	v_exp_f32_e32 v173, v173
	v_exp_f32_e32 v174, v174
	v_exp_f32_e32 v175, v175
	v_add_f32_e32 v172, 1.0, v172
	v_add_f32_e32 v173, 1.0, v173
	v_add_f32_e32 v174, 1.0, v174
	v_add_f32_e32 v175, 1.0, v175
	v_rcp_f32_e32 v172, v172
	v_rcp_f32_e32 v173, v173
	v_rcp_f32_e32 v174, v174
	v_rcp_f32_e32 v175, v175
	s_nop 0
	v_pk_fma_f32 v[110:111], v[6:7], v[172:173], v[110:111]
	v_pk_fma_f32 v[108:109], v[8:9], v[174:175], v[108:109]
	ds_read_u16 v190, v244 offset:64
	ds_read_u16 v191, v244 offset:192
	ds_read_u16 v192, v245 offset:320
	ds_read_u16 v193, v245 offset:448
	ds_read_u16 v194, v244 offset:1024
	ds_read_u16 v195, v244 offset:1152
	ds_read_u16 v196, v245 offset:1280
	ds_read_u16 v197, v245 offset:1408
	s_waitcnt lgkmcnt(8)
	v_lshlrev_b32_e32 v176, 16, v176
	v_lshlrev_b32_e32 v177, 16, v177
	v_lshlrev_b32_e32 v178, 16, v178
	v_lshlrev_b32_e32 v179, 16, v179
	v_mul_f32_e32 v176, 0xbfb8aa3b, v176
	v_mul_f32_e32 v177, 0xbfb8aa3b, v177
	v_mul_f32_e32 v178, 0xbfb8aa3b, v178
	v_mul_f32_e32 v179, 0xbfb8aa3b, v179
	v_exp_f32_e32 v176, v176
	v_exp_f32_e32 v177, v177
	v_exp_f32_e32 v178, v178
	v_exp_f32_e32 v179, v179
	v_add_f32_e32 v176, 1.0, v176
	v_add_f32_e32 v177, 1.0, v177
	v_add_f32_e32 v178, 1.0, v178
	v_add_f32_e32 v179, 1.0, v179
	v_rcp_f32_e32 v176, v176
	v_rcp_f32_e32 v177, v177
	v_rcp_f32_e32 v178, v178
	v_rcp_f32_e32 v179, v179
	s_nop 0
	v_pk_fma_f32 v[106:107], v[10:11], v[176:177], v[106:107]
	v_pk_fma_f32 v[104:105], v[12:13], v[178:179], v[104:105]
	v_lshlrev_b32_e32 v180, 16, v180
	v_lshlrev_b32_e32 v181, 16, v181
	v_lshlrev_b32_e32 v182, 16, v182
	v_lshlrev_b32_e32 v183, 16, v183
	v_mul_f32_e32 v180, 0xbfb8aa3b, v180
	v_mul_f32_e32 v181, 0xbfb8aa3b, v181
	v_mul_f32_e32 v182, 0xbfb8aa3b, v182
	v_mul_f32_e32 v183, 0xbfb8aa3b, v183
	v_exp_f32_e32 v180, v180
	v_exp_f32_e32 v181, v181
	v_exp_f32_e32 v182, v182
	v_exp_f32_e32 v183, v183
	v_add_f32_e32 v180, 1.0, v180
	v_add_f32_e32 v181, 1.0, v181
	v_add_f32_e32 v182, 1.0, v182
	v_add_f32_e32 v183, 1.0, v183
	v_rcp_f32_e32 v180, v180
	v_rcp_f32_e32 v181, v181
	v_rcp_f32_e32 v182, v182
	v_rcp_f32_e32 v183, v183
	s_nop 0
	v_pk_fma_f32 v[102:103], v[14:15], v[180:181], v[102:103]
	v_pk_fma_f32 v[100:101], v[16:17], v[182:183], v[100:101]
	ds_read_u16 v198, v244 offset:2112
	ds_read_u16 v199, v244 offset:2240
	ds_read_u16 v200, v245 offset:2368
	ds_read_u16 v201, v245 offset:2496
	ds_read_u16 v202, v244 offset:3072
	ds_read_u16 v203, v244 offset:3200
	ds_read_u16 v204, v245 offset:3328
	ds_read_u16 v205, v245 offset:3456
	s_waitcnt lgkmcnt(8)
	v_lshlrev_b32_e32 v190, 16, v190
	v_lshlrev_b32_e32 v191, 16, v191
	v_lshlrev_b32_e32 v192, 16, v192
	v_lshlrev_b32_e32 v193, 16, v193
	v_mul_f32_e32 v190, 0xbfb8aa3b, v190
	v_mul_f32_e32 v191, 0xbfb8aa3b, v191
	v_mul_f32_e32 v192, 0xbfb8aa3b, v192
	v_mul_f32_e32 v193, 0xbfb8aa3b, v193
	v_exp_f32_e32 v190, v190
	v_exp_f32_e32 v191, v191
	v_exp_f32_e32 v192, v192
	v_exp_f32_e32 v193, v193
	v_add_f32_e32 v190, 1.0, v190
	v_add_f32_e32 v191, 1.0, v191
	v_add_f32_e32 v192, 1.0, v192
	v_add_f32_e32 v193, 1.0, v193
	v_rcp_f32_e32 v190, v190
	v_rcp_f32_e32 v191, v191
	v_rcp_f32_e32 v192, v192
	v_rcp_f32_e32 v193, v193
	s_nop 0
	v_pk_fma_f32 v[150:151], v[34:35], v[190:191], v[150:151]
	v_pk_fma_f32 v[148:149], v[36:37], v[192:193], v[148:149]
	v_lshlrev_b32_e32 v194, 16, v194
	v_lshlrev_b32_e32 v195, 16, v195
	v_lshlrev_b32_e32 v196, 16, v196
	v_lshlrev_b32_e32 v197, 16, v197
	v_mul_f32_e32 v194, 0xbfb8aa3b, v194
	v_mul_f32_e32 v195, 0xbfb8aa3b, v195
	v_mul_f32_e32 v196, 0xbfb8aa3b, v196
	v_mul_f32_e32 v197, 0xbfb8aa3b, v197
	v_exp_f32_e32 v194, v194
	v_exp_f32_e32 v195, v195
	v_exp_f32_e32 v196, v196
	v_exp_f32_e32 v197, v197
	v_add_f32_e32 v194, 1.0, v194
	v_add_f32_e32 v195, 1.0, v195
	v_add_f32_e32 v196, 1.0, v196
	v_add_f32_e32 v197, 1.0, v197
	v_rcp_f32_e32 v194, v194
	v_rcp_f32_e32 v195, v195
	v_rcp_f32_e32 v196, v196
	v_rcp_f32_e32 v197, v197
	s_nop 0
	v_pk_fma_f32 v[146:147], v[38:39], v[194:195], v[146:147]
	v_pk_fma_f32 v[142:143], v[40:41], v[196:197], v[142:143]
	s_waitcnt lgkmcnt(0)
	v_lshlrev_b32_e32 v198, 16, v198
	v_lshlrev_b32_e32 v199, 16, v199
	v_lshlrev_b32_e32 v200, 16, v200
	v_lshlrev_b32_e32 v201, 16, v201
	v_mul_f32_e32 v198, 0xbfb8aa3b, v198
	v_mul_f32_e32 v199, 0xbfb8aa3b, v199
	v_mul_f32_e32 v200, 0xbfb8aa3b, v200
	v_mul_f32_e32 v201, 0xbfb8aa3b, v201
	v_exp_f32_e32 v198, v198
	v_exp_f32_e32 v199, v199
	v_exp_f32_e32 v200, v200
	v_exp_f32_e32 v201, v201
	v_add_f32_e32 v198, 1.0, v198
	v_add_f32_e32 v199, 1.0, v199
	v_add_f32_e32 v200, 1.0, v200
	v_add_f32_e32 v201, 1.0, v201
	v_rcp_f32_e32 v198, v198
	v_rcp_f32_e32 v199, v199
	v_rcp_f32_e32 v200, v200
	v_rcp_f32_e32 v201, v201
	s_nop 0
	v_pk_fma_f32 v[140:141], v[42:43], v[198:199], v[140:141]
	v_pk_fma_f32 v[138:139], v[44:45], v[200:201], v[138:139]
	v_lshlrev_b32_e32 v202, 16, v202
	v_lshlrev_b32_e32 v203, 16, v203
	v_lshlrev_b32_e32 v204, 16, v204
	v_lshlrev_b32_e32 v205, 16, v205
	v_mul_f32_e32 v202, 0xbfb8aa3b, v202
	v_mul_f32_e32 v203, 0xbfb8aa3b, v203
	v_mul_f32_e32 v204, 0xbfb8aa3b, v204
	v_mul_f32_e32 v205, 0xbfb8aa3b, v205
	v_exp_f32_e32 v202, v202
	v_exp_f32_e32 v203, v203
	v_exp_f32_e32 v204, v204
	v_exp_f32_e32 v205, v205
	v_add_f32_e32 v202, 1.0, v202
	v_add_f32_e32 v203, 1.0, v203
	v_add_f32_e32 v204, 1.0, v204
	v_add_f32_e32 v205, 1.0, v205
	v_rcp_f32_e32 v202, v202
	v_rcp_f32_e32 v203, v203
	v_rcp_f32_e32 v204, v204
	v_rcp_f32_e32 v205, v205
	s_nop 0
	v_pk_fma_f32 v[136:137], v[46:47], v[202:203], v[136:137]
	v_pk_fma_f32 v[134:135], v[48:49], v[204:205], v[134:135]
	v_readlane_b32 s36, v252, 4
	v_readlane_b32 s37, v252, 5
	v_readlane_b32 s38, v252, 6
	v_readlane_b32 s39, v252, 7
	v_readlane_b32 s40, v252, 8
	v_readlane_b32 s41, v252, 9
	v_readlane_b32 s42, v252, 10
	v_readlane_b32 s43, v252, 11
	v_readlane_b32 s44, v252, 12
	v_readlane_b32 s45, v252, 13
	v_readlane_b32 s46, v252, 14
	v_readlane_b32 s47, v252, 15
	v_readlane_b32 s48, v252, 16
	v_readlane_b32 s49, v252, 17
	s_mov_b32 s94, 0x9425000
	s_mov_b32 s25, 0xa8000
	s_movk_i32 s26, 0x600
	s_movk_i32 s27, 0x80
	v_cvt_pk_bf16_f32 v0, v166, s0
	s_barrier
	ds_write_b16 v98, v0
	v_cvt_pk_bf16_f32 v0, v167, s0
	ds_write_b16 v98, v0 offset:272
	v_cvt_pk_bf16_f32 v0, v164, s0
	ds_write_b16 v98, v0 offset:544
	v_cvt_pk_bf16_f32 v0, v165, s0
	ds_write_b16 v98, v0 offset:816
	v_cvt_pk_bf16_f32 v0, v162, s0
	ds_write_b16 v98, v0 offset:2176
	v_cvt_pk_bf16_f32 v0, v163, s0
	ds_write_b16 v98, v0 offset:2448
	v_cvt_pk_bf16_f32 v0, v160, s0
	ds_write_b16 v98, v0 offset:2720
	v_cvt_pk_bf16_f32 v0, v161, s0
	ds_write_b16 v98, v0 offset:2992
	v_cvt_pk_bf16_f32 v0, v158, s0
	ds_write_b16 v98, v0 offset:4352
	v_cvt_pk_bf16_f32 v0, v159, s0
	ds_write_b16 v98, v0 offset:4624
	v_cvt_pk_bf16_f32 v0, v156, s0
	ds_write_b16 v98, v0 offset:4896
	v_cvt_pk_bf16_f32 v0, v157, s0
	ds_write_b16 v98, v0 offset:5168
	v_cvt_pk_bf16_f32 v0, v154, s0
	ds_write_b16 v98, v0 offset:6528
	v_cvt_pk_bf16_f32 v0, v155, s0
	ds_write_b16 v98, v0 offset:6800
	v_cvt_pk_bf16_f32 v0, v152, s0
	ds_write_b16 v98, v0 offset:7072
	v_cvt_pk_bf16_f32 v0, v153, s0
	ds_write_b16 v98, v0 offset:7344
	v_cvt_pk_bf16_f32 v0, v150, s0
	ds_write_b16 v98, v0 offset:64
	v_cvt_pk_bf16_f32 v0, v151, s0
	ds_write_b16 v98, v0 offset:336
	v_cvt_pk_bf16_f32 v0, v148, s0
	ds_write_b16 v98, v0 offset:608
	v_cvt_pk_bf16_f32 v0, v149, s0
	ds_write_b16 v98, v0 offset:880
	v_cvt_pk_bf16_f32 v0, v146, s0
	ds_write_b16 v98, v0 offset:2240
	v_cvt_pk_bf16_f32 v0, v147, s0
	ds_write_b16 v98, v0 offset:2512
	v_cvt_pk_bf16_f32 v0, v142, s0
	ds_write_b16 v98, v0 offset:2784
	v_cvt_pk_bf16_f32 v0, v143, s0
	ds_write_b16 v98, v0 offset:3056
	v_cvt_pk_bf16_f32 v0, v140, s0
	ds_write_b16 v98, v0 offset:4416
	v_cvt_pk_bf16_f32 v0, v141, s0
	ds_write_b16 v98, v0 offset:4688
	v_cvt_pk_bf16_f32 v0, v138, s0
	ds_write_b16 v98, v0 offset:4960
	v_cvt_pk_bf16_f32 v0, v139, s0
	ds_write_b16 v98, v0 offset:5232
	v_cvt_pk_bf16_f32 v0, v136, s0
	ds_write_b16 v98, v0 offset:6592
	v_cvt_pk_bf16_f32 v0, v137, s0
	ds_write_b16 v98, v0 offset:6864
	v_cvt_pk_bf16_f32 v0, v134, s0
	ds_write_b16 v98, v0 offset:7136
	v_cvt_pk_bf16_f32 v0, v135, s0
	ds_write_b16 v98, v0 offset:7408
	v_cvt_pk_bf16_f32 v0, v130, s0
	ds_write_b16 v98, v0 offset:8704
	v_cvt_pk_bf16_f32 v0, v131, s0
	ds_write_b16 v98, v0 offset:8976
	v_cvt_pk_bf16_f32 v0, v128, s0
	ds_write_b16 v98, v0 offset:9248
	v_cvt_pk_bf16_f32 v0, v129, s0
	ds_write_b16 v98, v0 offset:9520
	v_cvt_pk_bf16_f32 v0, v126, s0
	ds_write_b16 v98, v0 offset:10880
	v_cvt_pk_bf16_f32 v0, v127, s0
	ds_write_b16 v98, v0 offset:11152
	v_cvt_pk_bf16_f32 v0, v124, s0
	ds_write_b16 v98, v0 offset:11424
	v_cvt_pk_bf16_f32 v0, v125, s0
	ds_write_b16 v98, v0 offset:11696
	v_cvt_pk_bf16_f32 v0, v122, s0
	ds_write_b16 v98, v0 offset:13056
	v_cvt_pk_bf16_f32 v0, v123, s0
	ds_write_b16 v98, v0 offset:13328
	v_cvt_pk_bf16_f32 v0, v120, s0
	ds_write_b16 v98, v0 offset:13600
	v_cvt_pk_bf16_f32 v0, v121, s0
	ds_write_b16 v98, v0 offset:13872
	v_cvt_pk_bf16_f32 v0, v118, s0
	ds_write_b16 v98, v0 offset:15232
	v_cvt_pk_bf16_f32 v0, v119, s0
	ds_write_b16 v98, v0 offset:15504
	v_cvt_pk_bf16_f32 v0, v116, s0
	ds_write_b16 v98, v0 offset:15776
	v_cvt_pk_bf16_f32 v0, v117, s0
	ds_write_b16 v98, v0 offset:16048
	v_cvt_pk_bf16_f32 v0, v114, s0
	ds_write_b16 v98, v0 offset:8768
	v_cvt_pk_bf16_f32 v0, v115, s0
	ds_write_b16 v98, v0 offset:9040
	v_cvt_pk_bf16_f32 v0, v112, s0
	ds_write_b16 v98, v0 offset:9312
	v_cvt_pk_bf16_f32 v0, v113, s0
	ds_write_b16 v98, v0 offset:9584
	v_cvt_pk_bf16_f32 v0, v110, s0
	ds_write_b16 v98, v0 offset:10944
	v_cvt_pk_bf16_f32 v0, v111, s0
	ds_write_b16 v98, v0 offset:11216
	v_cvt_pk_bf16_f32 v0, v108, s0
	ds_write_b16 v98, v0 offset:11488
	v_cvt_pk_bf16_f32 v0, v109, s0
	ds_write_b16 v98, v0 offset:11760
	v_cvt_pk_bf16_f32 v0, v106, s0
	ds_write_b16 v98, v0 offset:13120
	v_cvt_pk_bf16_f32 v0, v107, s0
	ds_write_b16 v98, v0 offset:13392
	v_cvt_pk_bf16_f32 v0, v104, s0
	ds_write_b16 v98, v0 offset:13664
	v_cvt_pk_bf16_f32 v0, v105, s0
	ds_write_b16 v98, v0 offset:13936
	v_cvt_pk_bf16_f32 v0, v102, s0
	ds_write_b16 v98, v0 offset:15296
	v_cvt_pk_bf16_f32 v0, v103, s0
	ds_write_b16 v98, v0 offset:15568
	v_cvt_pk_bf16_f32 v0, v100, s0
	ds_write_b16 v98, v0 offset:15840
	v_cvt_pk_bf16_f32 v0, v101, s0
	ds_write_b16 v98, v0 offset:16112
	s_waitcnt lgkmcnt(0)
	s_barrier
	ds_read_b128 v[2:5], v133
	ds_read_b128 v[6:9], v133 offset:4352
	s_lshl_b32 s24, s99, 7
	s_and_b32 s24, s24, 0x380
	v_add_lshl_u32 v0, v184, s23, 10
	v_or3_b32 v0, v185, s24, v0
	v_lshl_add_u64 v[10:11], v[0:1], 1, s[72:73]
	s_waitcnt lgkmcnt(1)
	global_store_dwordx4 v[10:11], v[2:5], off
	v_readlane_b32 s23, v254, 37
	s_add_i32 s20, s20, s23
	v_add_u32_e32 v2, 0x4000, v0
	v_mov_b32_e32 v3, v1
	v_lshl_add_u64 v[2:3], v[2:3], 1, s[72:73]
	s_waitcnt lgkmcnt(0)
	global_store_dwordx4 v[2:3], v[6:9], off
	ds_read_b128 v[2:5], v133 offset:8704
	v_readlane_b32 s23, v254, 36
	v_add_u32_e32 v6, 0x8000, v0
	v_mov_b32_e32 v7, v1
	v_lshl_add_u64 v[10:11], v[6:7], 1, s[72:73]
	ds_read_b128 v[6:9], v133 offset:13056
	s_waitcnt lgkmcnt(1)
	global_store_dwordx4 v[10:11], v[2:5], off
	s_add_i32 s22, s22, s81
	s_add_i32 s21, s21, s23
	v_add_u32_e32 v2, 0xc000, v0
	v_mov_b32_e32 v3, v1
	v_lshl_add_u64 v[2:3], v[2:3], 1, s[72:73]
	s_waitcnt lgkmcnt(0)
	global_store_dwordx4 v[2:3], v[6:9], off
	ds_read_b128 v[2:5], v133 offset:17408
	s_cmpk_gt_i32 s22, 0x1ff
	v_add_u32_e32 v6, 0x10000, v0
	v_mov_b32_e32 v7, v1
	v_lshl_add_u64 v[10:11], v[6:7], 1, s[72:73]
	ds_read_b128 v[6:9], v133 offset:21760
	s_waitcnt lgkmcnt(1)
	global_store_dwordx4 v[10:11], v[2:5], off
	s_nop 1
	v_add_u32_e32 v2, 0x14000, v0
	v_mov_b32_e32 v3, v1
	v_lshl_add_u64 v[2:3], v[2:3], 1, s[72:73]
	s_waitcnt lgkmcnt(0)
	global_store_dwordx4 v[2:3], v[6:9], off
	ds_read_b128 v[2:5], v133 offset:26112
	s_nop 0
	v_add_u32_e32 v6, 0x18000, v0
	v_mov_b32_e32 v7, v1
	v_lshl_add_u64 v[10:11], v[6:7], 1, s[72:73]
	ds_read_b128 v[6:9], v133 offset:30464
	v_add_u32_e32 v0, 0x1c000, v0
	s_waitcnt lgkmcnt(1)
	global_store_dwordx4 v[10:11], v[2:5], off
	s_nop 1
	v_lshl_add_u64 v[2:3], v[0:1], 1, s[72:73]
	s_waitcnt lgkmcnt(0)
	global_store_dwordx4 v[2:3], v[6:9], off
	s_cbranch_scc0 .LBB0_212
	s_mov_b32 s19, 0x80000
	s_mov_b32 s14, 0xdb629599
	s_mov_b32 s15, 0xf534ddc0
	s_mov_b32 s16, 0xfc2757d1
	s_mov_b64 s[12:13], s[30:31]
	v_readlane_b32 s22, v255, 2
	v_mov_b32_e32 v187, 0x358637bd
	v_mov_b32_e32 v196, v189
	v_mov_b32_e32 v197, v214
	v_mov_b32_e32 v198, v215
	v_mov_b32_e32 v199, v218
	v_xor_b32_e32 v200, 16, v220
	v_xor_b32_e32 v201, 8, v220
	v_mov_b32_e32 v202, v219
	v_mov_b32_e32 v203, v229
	v_mov_b32_e32 v204, v230
	v_readlane_b32 s23, v255, 3
